# attention loop: counted lgkmcnt waits in QK and PV, l-sum adds moved into PV MFMA shadow, cross-half max via permlane32_swap; ssq loads hoisted in P6/P10 epilogues
# speedup vs baseline: 1.0036x; 1.0036x over previous
; #define LAS __attribute__((address_space(3)))
;     ...
;             const LAS unsigned char* kb_ = lds + ATT_KB + b * 16384;
;             const LAS unsigned char* vb_ = lds + ATT_VB + b * 16384;
;             f32x16 st[2];
;             bf16x8 ka[8];
; #pragma unroll
;             for (int ks = 0; ks < 8; ++ks) ka[ks] = *(const LAS bf16x8*)(kb_ + (kbase ^ (unsigned)(ks << 5)));
;             bf16x8 va[2][4];
; #pragma unroll
;             for (int dt = 0; dt < 4; ++dt) va[0][dt] = *(const LAS bf16x8*)(vb_ + dt * 4096 + vbase);
; #pragma unroll
;             for (int rt = 0; rt < 2; ++rt)
; #pragma unroll
;                 for (int r = 0; r < 16; ++r) st[rt][r] = 0.f;
;             __builtin_amdgcn_sched_barrier(0);
;             __builtin_amdgcn_s_setprio(1);
; #pragma unroll
;             for (int ks = 0; ks < 8; ++ks) { st[0] = __builtin_amdgcn_mfma_f32_32x32x16_bf16(ka[ks], qf[ks], st[0], 0, 0, 0);
;                 ka[ks] = *(const LAS bf16x8*)(kb_ + 8192 + (kbase ^ (unsigned)(ks << 5))); __builtin_amdgcn_sched_barrier(0); }
; #pragma unroll
;             for (int ks = 0; ks < 8; ++ks) st[1] = __builtin_amdgcn_mfma_f32_32x32x16_bf16(ka[ks], qf[ks], st[1], 0, 0, 0);
;             __builtin_amdgcn_s_setprio(0);
;             if (MOBA) {
;                 if (own && 64 * kt + 63 > 32 * w) {
;                     const int qloc = 32 * w + ql;
; #pragma unroll
;                     for (int rt = 0; rt < 2; ++rt)
; #pragma unroll
;                         for (int r = 0; r < 16; ++r) { const int key = 64 * kt + 32 * rt + 16 * (r >> 3) + 8 * h2 + (r & 7); if (key > qloc) st[rt][r] = NEGBIG; }
;                 }
.LBB0_413:
	s_lshl_b32 s34, s75, 14
	s_add_i32 s70, s34, 0
	v_add_u32_e32 v2, s70, v161
	v_add_u32_e32 v17, s70, v164
	v_add_u32_e32 v204, s70, v166
	v_add_u32_e32 v212, s70, v168
	v_add_u32_e32 v4, s70, v162
	v_add_u32_e32 v16, s70, v163
	ds_read_b128 v[82:85], v2
	ds_read_b128 v[98:101], v16
	v_add_u32_e32 v175, s70, v165
	ds_read_b128 v[102:105], v17
	ds_read_b128 v[106:109], v175
	v_add_u32_e32 v208, s70, v167
	ds_read_b128 v[110:113], v204
	ds_read_b128 v[176:179], v208
	v_add_u32_e32 v213, s70, v169
	ds_read_b128 v[180:183], v212
	ds_read_b128 v[184:187], v213
	ds_read_b128 v[146:149], v4 offset:49152
	ds_read_b128 v[12:15], v4 offset:53248
	ds_read_b128 v[8:11], v4 offset:57344
	ds_read_b128 v[4:7], v4 offset:61440
	s_setprio 1
	s_waitcnt lgkmcnt(11)
	v_mfma_f32_32x32x16_bf16 v[82:97], v[82:85], v[114:117], 0
	ds_read_b128 v[188:191], v2 offset:8192
	s_waitcnt lgkmcnt(11)
	v_mfma_f32_32x32x16_bf16 v[82:97], v[98:101], v[118:121], v[82:97]
	ds_read_b128 v[192:195], v16 offset:8192
	s_waitcnt lgkmcnt(11)
	v_mfma_f32_32x32x16_bf16 v[82:97], v[102:105], v[122:125], v[82:97]
	ds_read_b128 v[196:199], v17 offset:8192
	s_waitcnt lgkmcnt(11)
	v_mfma_f32_32x32x16_bf16 v[82:97], v[106:109], v[126:129], v[82:97]
	ds_read_b128 v[200:203], v175 offset:8192
	s_waitcnt lgkmcnt(11)
	v_mfma_f32_32x32x16_bf16 v[82:97], v[110:113], v[130:133], v[82:97]
	ds_read_b128 v[204:207], v204 offset:8192
	s_waitcnt lgkmcnt(11)
	v_mfma_f32_32x32x16_bf16 v[82:97], v[176:179], v[134:137], v[82:97]
	ds_read_b128 v[208:211], v208 offset:8192
	s_waitcnt lgkmcnt(11)
	v_mfma_f32_32x32x16_bf16 v[82:97], v[180:183], v[138:141], v[82:97]
	ds_read_b128 v[176:179], v212 offset:8192
	s_waitcnt lgkmcnt(11)
	v_mfma_f32_32x32x16_bf16 v[82:97], v[184:187], v[142:145], v[82:97]
	ds_read_b128 v[180:183], v213 offset:8192
	s_waitcnt lgkmcnt(7)
	v_mfma_f32_32x32x16_bf16 v[98:113], v[188:191], v[114:117], 0
	s_waitcnt lgkmcnt(6)
	v_mfma_f32_32x32x16_bf16 v[98:113], v[192:195], v[118:121], v[98:113]
	s_waitcnt lgkmcnt(5)
	v_mfma_f32_32x32x16_bf16 v[98:113], v[196:199], v[122:125], v[98:113]
	s_waitcnt lgkmcnt(4)
	v_mfma_f32_32x32x16_bf16 v[98:113], v[200:203], v[126:129], v[98:113]
	s_waitcnt lgkmcnt(3)
	v_mfma_f32_32x32x16_bf16 v[98:113], v[204:207], v[130:133], v[98:113]
	s_waitcnt lgkmcnt(2)
	v_mfma_f32_32x32x16_bf16 v[98:113], v[208:211], v[134:137], v[98:113]
	s_waitcnt lgkmcnt(1)
	v_mfma_f32_32x32x16_bf16 v[98:113], v[176:179], v[138:141], v[98:113]
	s_waitcnt lgkmcnt(0)
	v_mfma_f32_32x32x16_bf16 v[98:113], v[180:183], v[142:145], v[98:113]
	s_setprio 0
	s_or_b32 s34, s72, 63
	s_cmp_gt_i32 s34, s96
	s_cselect_b64 s[34:35], -1, 0
	s_and_b64 s[34:35], s[68:69], s[34:35]
	s_andn2_b64 vcc, exec, s[34:35]
	s_cbranch_vccnz .LBB0_415
	v_or_b32_e32 v2, s72, v155
	v_cmp_gt_i32_e32 vcc, v2, v154
	s_nop 1
	v_cndmask_b32_e32 v16, v82, v232, vcc
	v_cmp_lt_i32_e32 vcc, v2, v154
	s_nop 1
	v_cndmask_b32_e32 v82, v16, v82, vcc
	v_or_b32_e32 v16, 2, v2
	v_cndmask_b32_e32 v83, v232, v83, vcc
	v_cmp_le_i32_e32 vcc, v16, v154
	v_or_b32_e32 v16, 3, v2
	s_nop 0
	v_cndmask_b32_e32 v84, v232, v84, vcc
	v_cmp_le_i32_e32 vcc, v16, v154
	v_or_b32_e32 v16, 4, v2
	s_nop 0
	v_cndmask_b32_e32 v85, v232, v85, vcc
	v_cmp_le_i32_e32 vcc, v16, v154
	v_or_b32_e32 v16, 5, v2
	s_nop 0
	v_cndmask_b32_e32 v86, v232, v86, vcc
	v_cmp_le_i32_e32 vcc, v16, v154
	v_or_b32_e32 v16, 6, v2
	s_nop 0
	v_cndmask_b32_e32 v87, v232, v87, vcc
	v_cmp_le_i32_e32 vcc, v16, v154
	v_or_b32_e32 v16, 7, v2
	s_nop 0
	v_cndmask_b32_e32 v88, v232, v88, vcc
	v_cmp_le_i32_e32 vcc, v16, v154
	v_or_b32_e32 v16, 16, v2
	s_nop 0
	v_cndmask_b32_e32 v89, v232, v89, vcc
	v_cmp_le_i32_e32 vcc, v16, v154
	v_or_b32_e32 v16, 17, v2
	s_nop 0
	v_cndmask_b32_e32 v90, v232, v90, vcc
	v_cmp_le_i32_e32 vcc, v16, v154
	v_or_b32_e32 v16, 18, v2
	s_nop 0
	v_cndmask_b32_e32 v91, v232, v91, vcc
	v_cmp_le_i32_e32 vcc, v16, v154
	v_or_b32_e32 v16, 19, v2
	s_nop 0
	v_cndmask_b32_e32 v92, v232, v92, vcc
	v_cmp_le_i32_e32 vcc, v16, v154
	v_or_b32_e32 v16, 20, v2
	s_nop 0
	v_cndmask_b32_e32 v93, v232, v93, vcc
	v_cmp_le_i32_e32 vcc, v16, v154
	v_or_b32_e32 v16, 21, v2
	s_nop 0
	v_cndmask_b32_e32 v94, v232, v94, vcc
	v_cmp_le_i32_e32 vcc, v16, v154
	v_or_b32_e32 v16, 22, v2
	s_nop 0
	v_cndmask_b32_e32 v95, v232, v95, vcc
	v_cmp_le_i32_e32 vcc, v16, v154
	v_or_b32_e32 v16, 23, v2
	s_nop 0
	v_cndmask_b32_e32 v96, v232, v96, vcc
	v_cmp_le_i32_e32 vcc, v16, v154
	v_or_b32_e32 v16, 32, v2
	s_nop 0
	v_cndmask_b32_e32 v97, v232, v97, vcc
	v_cmp_le_i32_e32 vcc, v16, v154
	v_or_b32_e32 v16, 33, v2
	s_nop 0
	v_cndmask_b32_e32 v98, v232, v98, vcc
	v_cmp_le_i32_e32 vcc, v16, v154
	v_or_b32_e32 v16, 34, v2
	s_nop 0
	v_cndmask_b32_e32 v99, v232, v99, vcc
	v_cmp_le_i32_e32 vcc, v16, v154
	v_or_b32_e32 v16, 35, v2
	s_nop 0
	v_cndmask_b32_e32 v100, v232, v100, vcc
	v_cmp_le_i32_e32 vcc, v16, v154
	v_or_b32_e32 v16, 36, v2
	s_nop 0
	v_cndmask_b32_e32 v101, v232, v101, vcc
	v_cmp_le_i32_e32 vcc, v16, v154
	v_or_b32_e32 v16, 37, v2
	s_nop 0
	v_cndmask_b32_e32 v102, v232, v102, vcc
	v_cmp_le_i32_e32 vcc, v16, v154
	v_or_b32_e32 v16, 38, v2
	s_nop 0
	v_cndmask_b32_e32 v103, v232, v103, vcc
	v_cmp_le_i32_e32 vcc, v16, v154
	v_or_b32_e32 v16, 39, v2
	s_nop 0
	v_cndmask_b32_e32 v104, v232, v104, vcc
	v_cmp_le_i32_e32 vcc, v16, v154
	v_or_b32_e32 v16, 48, v2
	s_nop 0
	v_cndmask_b32_e32 v105, v232, v105, vcc
	v_cmp_le_i32_e32 vcc, v16, v154
	v_or_b32_e32 v16, 49, v2
	s_nop 0
	v_cndmask_b32_e32 v106, v232, v106, vcc
	v_cmp_le_i32_e32 vcc, v16, v154
	v_or_b32_e32 v16, 50, v2
	s_nop 0
	v_cndmask_b32_e32 v107, v232, v107, vcc
	v_cmp_le_i32_e32 vcc, v16, v154
	v_or_b32_e32 v16, 51, v2
	s_nop 0
	v_cndmask_b32_e32 v108, v232, v108, vcc
	v_cmp_le_i32_e32 vcc, v16, v154
	v_or_b32_e32 v16, 52, v2
	s_nop 0
	v_cndmask_b32_e32 v109, v232, v109, vcc
	v_cmp_le_i32_e32 vcc, v16, v154
	v_or_b32_e32 v16, 53, v2
	s_nop 0
	v_cndmask_b32_e32 v110, v232, v110, vcc
	v_cmp_le_i32_e32 vcc, v16, v154
	v_or_b32_e32 v16, 54, v2
	v_or_b32_e32 v2, 55, v2
	v_cndmask_b32_e32 v111, v232, v111, vcc
	v_cmp_le_i32_e32 vcc, v16, v154
	s_nop 1
	v_cndmask_b32_e32 v112, v232, v112, vcc
	v_cmp_le_i32_e32 vcc, v2, v154
	s_nop 1
	v_cndmask_b32_e32 v113, v232, v113, vcc
;     ...
;             float mx = st[0][0];
; #pragma unroll
;             for (int rt = 0; rt < 2; ++rt)
; #pragma unroll
;                 for (int r = 0; r < 16; ++r) mx = fmaxf(mx, st[rt][r]);
;             if (MOBA) mx = selme ? mx : NEGBIG;
;             mx = fmaxf(mx, __shfl_xor(mx, 32));
;             if (__builtin_amdgcn_ballot_w64(mx > mrow + 8.0f) != 0ull) {
;                 const float mnew = fmaxf(mrow, mx), alpha = __builtin_amdgcn_exp2f(mrow - mnew);
;                 mrow = mnew; lsum *= alpha;
; #pragma unroll
;                 for (int dt = 0; dt < 4; ++dt)
; #pragma unroll
;                     for (int r = 0; r < 16; ++r) ot[dt][r] *= alpha;
;             }
.LBB0_415:
	v_max_f32_e32 v2, v83, v83
	v_max_f32_e32 v16, v82, v82
	v_max_f32_e32 v2, v16, v2
	v_max3_f32 v2, v2, v84, v85
	v_max3_f32 v2, v2, v86, v87
	v_max3_f32 v2, v2, v88, v89
	v_max3_f32 v2, v2, v90, v91
	v_max3_f32 v2, v2, v92, v93
	v_max3_f32 v2, v2, v94, v95
	v_max3_f32 v2, v2, v96, v97
	v_max3_f32 v2, v2, v98, v99
	v_max3_f32 v2, v2, v100, v101
	v_max3_f32 v2, v2, v102, v103
	v_max3_f32 v2, v2, v104, v105
	v_max3_f32 v2, v2, v106, v107
	v_and_b32_e32 v17, 64, v1
	v_max3_f32 v2, v2, v108, v109
	v_xor_b32_e32 v16, 32, v1
	v_add_u32_e32 v17, 64, v17
	v_max3_f32 v2, v2, v110, v111
	v_cmp_lt_i32_e32 vcc, v16, v17
	v_max3_f32 v2, v2, v112, v113
	v_cndmask_b32_e64 v2, v232, v2, s[2:3]
	v_cndmask_b32_e32 v16, v1, v16, vcc
	v_lshlrev_b32_e32 v16, 2, v16
	v_mov_b32_e32 v16, v2
	s_nop 1
	v_permlane32_swap_b32_e32 v16, v2
	v_max_f32_e32 v16, v16, v16
	v_max_f32_e32 v2, v2, v16
	v_add_f32_e32 v16, 0x41000000, v174
	v_cmp_gt_f32_e32 vcc, v2, v16
	s_cbranch_vccz .LBB0_417
	v_max_f32_e32 v2, v2, v2
	v_max_f32_e32 v16, v174, v174
	v_max_f32_e32 v16, v16, v2
	v_sub_f32_e32 v2, v174, v16
	v_exp_f32_e32 v2, v2
	v_mov_b32_e32 v174, v16
	v_pk_mul_f32 v[80:81], v[80:81], v[2:3] op_sel_hi:[1,0]
	v_pk_mul_f32 v[78:79], v[78:79], v[2:3] op_sel_hi:[1,0]
	v_pk_mul_f32 v[76:77], v[76:77], v[2:3] op_sel_hi:[1,0]
	v_pk_mul_f32 v[74:75], v[74:75], v[2:3] op_sel_hi:[1,0]
	v_pk_mul_f32 v[72:73], v[72:73], v[2:3] op_sel_hi:[1,0]
	v_pk_mul_f32 v[70:71], v[70:71], v[2:3] op_sel_hi:[1,0]
	v_pk_mul_f32 v[68:69], v[68:69], v[2:3] op_sel_hi:[1,0]
	v_pk_mul_f32 v[66:67], v[66:67], v[2:3] op_sel_hi:[1,0]
	v_pk_mul_f32 v[64:65], v[64:65], v[2:3] op_sel_hi:[1,0]
	v_pk_mul_f32 v[62:63], v[62:63], v[2:3] op_sel_hi:[1,0]
	v_pk_mul_f32 v[60:61], v[60:61], v[2:3] op_sel_hi:[1,0]
	v_pk_mul_f32 v[58:59], v[58:59], v[2:3] op_sel_hi:[1,0]
	v_pk_mul_f32 v[56:57], v[56:57], v[2:3] op_sel_hi:[1,0]
	v_pk_mul_f32 v[54:55], v[54:55], v[2:3] op_sel_hi:[1,0]
	v_pk_mul_f32 v[52:53], v[52:53], v[2:3] op_sel_hi:[1,0]
	v_pk_mul_f32 v[50:51], v[50:51], v[2:3] op_sel_hi:[1,0]
	v_pk_mul_f32 v[48:49], v[48:49], v[2:3] op_sel_hi:[1,0]
	v_pk_mul_f32 v[46:47], v[46:47], v[2:3] op_sel_hi:[1,0]
	v_pk_mul_f32 v[44:45], v[44:45], v[2:3] op_sel_hi:[1,0]
	v_pk_mul_f32 v[42:43], v[42:43], v[2:3] op_sel_hi:[1,0]
	v_pk_mul_f32 v[40:41], v[40:41], v[2:3] op_sel_hi:[1,0]
	v_pk_mul_f32 v[38:39], v[38:39], v[2:3] op_sel_hi:[1,0]
	v_pk_mul_f32 v[36:37], v[36:37], v[2:3] op_sel_hi:[1,0]
	v_pk_mul_f32 v[34:35], v[34:35], v[2:3] op_sel_hi:[1,0]
	v_pk_mul_f32 v[32:33], v[32:33], v[2:3] op_sel_hi:[1,0]
	v_pk_mul_f32 v[30:31], v[30:31], v[2:3] op_sel_hi:[1,0]
	v_pk_mul_f32 v[28:29], v[28:29], v[2:3] op_sel_hi:[1,0]
	v_pk_mul_f32 v[26:27], v[26:27], v[2:3] op_sel_hi:[1,0]
	v_pk_mul_f32 v[24:25], v[24:25], v[2:3] op_sel_hi:[1,0]
	v_pk_mul_f32 v[22:23], v[22:23], v[2:3] op_sel_hi:[1,0]
	v_pk_mul_f32 v[20:21], v[20:21], v[2:3] op_sel_hi:[1,0]
	v_pk_mul_f32 v[18:19], v[18:19], v[2:3] op_sel_hi:[1,0]
	v_mul_f32_e32 v173, v173, v2
; #define LAS __attribute__((address_space(3)))
; __device__ __forceinline__ unsigned pk2(float lo, float hi) { return cvt_pk_bf16(lo, hi); }
;     ...
;             const float msub = (MOBA && !selme) ? 1e30f : mrow;
;             float ps = 0.f;
; #pragma unroll
;             for (int rt = 0; rt < 2; ++rt)
; #pragma unroll
;                 for (int r = 0; r < 16; ++r) { const float p = __builtin_amdgcn_exp2f(st[rt][r] - msub); st[rt][r] = p; ps += p; }
;             lsum += ps;
; #pragma unroll
;             for (int kk = 0; kk < 4; ++kk) {
;                 const int rt = kk >> 1, s = kk & 1;
;                 u32x4 pw; pw.x = pk2(st[rt][8 * s + 0], st[rt][8 * s + 1]); pw.y = pk2(st[rt][8 * s + 2], st[rt][8 * s + 3]); pw.z = pk2(st[rt][8 * s + 4], st[rt][8 * s + 5]); pw.w = pk2(st[rt][8 * s + 6], st[rt][8 * s + 7]);
;                 const bf16x8 pb = __builtin_bit_cast(bf16x8, pw);
;                 if (kk < 3) {
; #pragma unroll
;                     for (int dt = 0; dt < 4; ++dt) va[(kk + 1) & 1][dt] = *(const LAS bf16x8*)(vb_ + dt * 4096 + (vbase ^ (unsigned)((kk + 1) << 5)));
;                 }
;                 __builtin_amdgcn_s_setprio(1);
; #pragma unroll
;                 for (int dt = 0; dt < 4; ++dt) ot[dt] = __builtin_amdgcn_mfma_f32_32x32x16_bf16(va[kk & 1][dt], pb, ot[dt], 0, 0, 0);
;                 __builtin_amdgcn_s_setprio(0);
;                 __builtin_amdgcn_sched_barrier(0);
;             }
.LBB0_417:
	v_cndmask_b32_e64 v2, v233, v174, s[2:3]
	v_sub_f32_e32 v16, v82, v2
	v_exp_f32_e32 v16, v16
	v_sub_f32_e32 v17, v83, v2
	v_exp_f32_e32 v17, v17
	v_sub_f32_e32 v82, v84, v2
	v_exp_f32_e32 v84, v82
	v_sub_f32_e32 v82, v85, v2
	v_add_f32_e32 v83, 0, v16
	v_exp_f32_e32 v85, v82
	v_sub_f32_e32 v82, v86, v2
	v_exp_f32_e32 v86, v82
	v_add_f32_e32 v82, v17, v83
	v_sub_f32_e32 v83, v87, v2
	v_exp_f32_e32 v87, v83
	v_sub_f32_e32 v83, v88, v2
	v_add_f32_e32 v82, v84, v82
	v_exp_f32_e32 v88, v83
	v_sub_f32_e32 v83, v89, v2
	v_add_f32_e32 v82, v85, v82
	v_exp_f32_e32 v89, v83
	v_sub_f32_e32 v83, v90, v2
	v_add_f32_e32 v82, v86, v82
	v_exp_f32_e32 v175, v83
	v_sub_f32_e32 v83, v91, v2
	v_add_f32_e32 v82, v87, v82
	v_exp_f32_e32 v176, v83
	v_sub_f32_e32 v83, v92, v2
	v_add_f32_e32 v82, v88, v82
	v_exp_f32_e32 v177, v83
	v_sub_f32_e32 v83, v93, v2
	v_add_f32_e32 v82, v89, v82
	v_exp_f32_e32 v178, v83
	v_sub_f32_e32 v83, v94, v2
	v_add_f32_e32 v82, v175, v82
	v_exp_f32_e32 v179, v83
	v_add_f32_e32 v82, v176, v82
	v_add_f32_e32 v82, v177, v82
	v_add_f32_e32 v82, v178, v82
	v_add_f32_e32 v180, v179, v82
	v_sub_f32_e32 v82, v95, v2
	v_exp_f32_e32 v181, v82
	v_sub_f32_e32 v82, v96, v2
	v_exp_f32_e32 v182, v82
	v_sub_f32_e32 v82, v97, v2
	v_exp_f32_e32 v183, v82
	v_sub_f32_e32 v82, v98, v2
	v_exp_f32_e32 v184, v82
	v_sub_f32_e32 v82, v99, v2
	v_exp_f32_e32 v185, v82
	v_sub_f32_e32 v82, v100, v2
	v_exp_f32_e32 v186, v82
	v_sub_f32_e32 v82, v101, v2
	v_exp_f32_e32 v187, v82
	v_sub_f32_e32 v82, v102, v2
	v_exp_f32_e32 v188, v82
	v_sub_f32_e32 v82, v103, v2
	v_exp_f32_e32 v189, v82
	v_sub_f32_e32 v82, v104, v2
	v_exp_f32_e32 v190, v82
	v_sub_f32_e32 v82, v105, v2
	v_exp_f32_e32 v191, v82
	v_sub_f32_e32 v82, v106, v2
	v_exp_f32_e32 v106, v82
	v_sub_f32_e32 v82, v107, v2
	v_exp_f32_e32 v107, v82
	v_sub_f32_e32 v82, v108, v2
	v_exp_f32_e32 v108, v82
	v_sub_f32_e32 v82, v109, v2
	v_exp_f32_e32 v109, v82
	v_sub_f32_e32 v82, v110, v2
	v_exp_f32_e32 v110, v82
	v_sub_f32_e32 v82, v111, v2
	v_exp_f32_e32 v111, v82
	v_sub_f32_e32 v82, v112, v2
	v_exp_f32_e32 v112, v82
	v_cvt_pk_bf16_f32 v82, v16, v17
	v_add_u32_e32 v16, s70, v170
	v_cvt_pk_bf16_f32 v83, v84, v85
	v_cvt_pk_bf16_f32 v84, v86, v87
	v_cvt_pk_bf16_f32 v85, v88, v89
	ds_read_b128 v[86:89], v16 offset:49152
	ds_read_b128 v[90:93], v16 offset:53248
	ds_read_b128 v[94:97], v16 offset:57344
	ds_read_b128 v[98:101], v16 offset:61440
	v_add_f32_e32 v16, v181, v180
	v_sub_f32_e32 v2, v113, v2
	v_add_f32_e32 v16, v182, v16
	v_exp_f32_e32 v2, v2
	v_add_f32_e32 v16, v183, v16
	s_setprio 1
	v_mfma_f32_32x32x16_bf16 v[66:81], v[146:149], v[82:85], v[66:81]
	v_mfma_f32_32x32x16_bf16 v[50:65], v[12:15], v[82:85], v[50:65]
	v_mfma_f32_32x32x16_bf16 v[34:49], v[8:11], v[82:85], v[34:49]
	v_mfma_f32_32x32x16_bf16 v[18:33], v[4:7], v[82:85], v[18:33]
	s_setprio 0
	v_add_f32_e32 v214, v184, v16
	v_add_f32_e32 v214, v185, v214
	v_add_f32_e32 v214, v186, v214
	v_add_f32_e32 v214, v187, v214
	v_add_f32_e32 v214, v188, v214
	v_add_f32_e32 v214, v189, v214
	v_add_u32_e32 v17, s70, v171
	v_cvt_pk_bf16_f32 v4, v175, v176
	v_cvt_pk_bf16_f32 v5, v177, v178
	v_cvt_pk_bf16_f32 v6, v179, v181
	v_cvt_pk_bf16_f32 v7, v182, v183
	ds_read_b128 v[8:11], v17 offset:49152
	ds_read_b128 v[12:15], v17 offset:53248
	ds_read_b128 v[82:85], v17 offset:57344
	ds_read_b128 v[102:105], v17 offset:61440
	s_setprio 1
	s_waitcnt lgkmcnt(4)
	v_mfma_f32_32x32x16_bf16 v[66:81], v[86:89], v[4:7], v[66:81]
	v_mfma_f32_32x32x16_bf16 v[50:65], v[90:93], v[4:7], v[50:65]
	v_mfma_f32_32x32x16_bf16 v[34:49], v[94:97], v[4:7], v[34:49]
	v_mfma_f32_32x32x16_bf16 v[18:33], v[98:101], v[4:7], v[18:33]
	s_setprio 0
	v_add_f32_e32 v214, v190, v214
	v_add_f32_e32 v214, v191, v214
	v_add_f32_e32 v214, v106, v214
	v_add_f32_e32 v214, v107, v214
	v_add_f32_e32 v214, v108, v214
	v_add_f32_e32 v214, v109, v214
	v_add_u32_e32 v17, s70, v172
	v_cvt_pk_bf16_f32 v4, v184, v185
	v_cvt_pk_bf16_f32 v5, v186, v187
	v_cvt_pk_bf16_f32 v6, v188, v189
	v_cvt_pk_bf16_f32 v7, v190, v191
	ds_read_b128 v[86:89], v17 offset:49152
	ds_read_b128 v[90:93], v17 offset:53248
	ds_read_b128 v[94:97], v17 offset:57344
	ds_read_b128 v[98:101], v17 offset:61440
	s_setprio 1
	s_waitcnt lgkmcnt(4)
	v_mfma_f32_32x32x16_bf16 v[66:81], v[8:11], v[4:7], v[66:81]
	v_mfma_f32_32x32x16_bf16 v[50:65], v[12:15], v[4:7], v[50:65]
	v_mfma_f32_32x32x16_bf16 v[34:49], v[82:85], v[4:7], v[34:49]
	v_mfma_f32_32x32x16_bf16 v[18:33], v[102:105], v[4:7], v[18:33]
	s_setprio 0
	v_add_f32_e32 v214, v110, v214
	v_add_f32_e32 v214, v111, v214
	v_add_f32_e32 v214, v112, v214
	v_add_f32_e32 v214, v2, v214
	v_add_f32_e32 v173, v173, v214
	v_cvt_pk_bf16_f32 v4, v106, v107
	v_cvt_pk_bf16_f32 v5, v108, v109
	v_cvt_pk_bf16_f32 v6, v110, v111
	v_cvt_pk_bf16_f32 v7, v112, v2
	s_setprio 1
	s_waitcnt lgkmcnt(0)
	v_mfma_f32_32x32x16_bf16 v[66:81], v[86:89], v[4:7], v[66:81]
	v_mfma_f32_32x32x16_bf16 v[50:65], v[90:93], v[4:7], v[50:65]
	v_mfma_f32_32x32x16_bf16 v[34:49], v[94:97], v[4:7], v[34:49]
	v_mfma_f32_32x32x16_bf16 v[18:33], v[98:101], v[4:7], v[18:33]
	s_setprio 0
	s_mov_b64 s[2:3], -1
	s_and_b64 vcc, exec, s[66:67]
	s_cbranch_vccz .LBB0_410

; __device__ __forceinline__ void st8(bf16_t* p, const f32x4& a, const f32x4& b) { u32x4 w; w.x = pk2(a[0], a[1]); w.y = pk2(a[2], a[3]); w.z = pk2(b[0], b[1]); w.w = pk2(b[2], b[3]); *(u32x4*)p = w; }
;     __device__ __forceinline__ void operator()(const f32x4 (&acc)[2][2][4][2], const Unit& u, int wr, int wc, int fr, int fq) const {
;         const int row0 = u.pm * 256 + wr * 64 + fr, col0 = u.pn * 256 + wc * 32 + 8 * fq;
; #pragma unroll
;         for (int ai = 0; ai < 2; ++ai)
; #pragma unroll
;             for (int m = 0; m < 4; ++m) {
;                 const int row = row0 + ai * 128 + m * 16; const float rs = sc * (1.0f / sqrtf(ssq[row] * (1.f / D) + RMS_EPS));
;                 bf16_t* rp = O + (size_t)row * ldc + col0;
; #pragma unroll
;                 for (int bj = 0; bj < 2; ++bj) st8(rp + bj * 128, acc[ai][bj][m][0] * rs, acc[ai][bj][m][1] * rs);
;             }
;     }
.LBB0_737:
	v_lshl_add_u32 v152, s4, 8, v1
	v_ashrrev_i32_e32 v153, 31, v152
	v_lshl_add_u64 v[148:149], v[152:153], 2, s[14:15]
	global_load_dword v150, v[148:149], off
	global_load_dword v170, v[148:149], off offset:64
	global_load_dword v171, v[148:149], off offset:128
	global_load_dword v172, v[148:149], off offset:192
	global_load_dword v173, v[148:149], off offset:512
	global_load_dword v174, v[148:149], off offset:576
	global_load_dword v175, v[148:149], off offset:640
	global_load_dword v176, v[148:149], off offset:704
	v_lshl_or_b32 v146, s5, 8, v155
	v_ashrrev_i32_e32 v147, 31, v146
	v_lshlrev_b64 v[162:163], 10, v[152:153]
	s_mov_b32 s24, 0x20000
	s_waitcnt vmcnt(0)
	v_fmamk_f32 v150, v150, 0x3a000000, v159
	v_mul_f32_e32 v151, 0x4f800000, v150
	v_cmp_gt_f32_e32 vcc, s83, v150
	s_nop 1
	v_cndmask_b32_e32 v161, v150, v151, vcc
	v_sqrt_f32_e32 v164, v161
	v_lshlrev_b64 v[150:151], 1, v[146:147]
	v_lshl_add_u64 v[146:147], s[6:7], 0, v[162:163]
	v_lshl_add_u64 v[146:147], v[146:147], 0, v[150:151]
	v_add_u32_e32 v153, -1, v164
	v_add_u32_e32 v162, 1, v164
	v_fma_f32 v163, -v153, v164, v161
	v_fma_f32 v165, -v162, v164, v161
	v_cmp_ge_f32_e64 s[4:5], 0, v163
	s_nop 1
	v_cndmask_b32_e64 v153, v164, v153, s[4:5]
	v_cmp_lt_f32_e64 s[4:5], 0, v165
	s_nop 1
	v_cndmask_b32_e64 v153, v153, v162, s[4:5]
	v_mul_f32_e32 v162, 0x37800000, v153
	v_cndmask_b32_e32 v153, v153, v162, vcc
	v_cmp_class_f32_e32 vcc, v161, v160
	s_nop 1
	v_cndmask_b32_e32 v153, v153, v161, vcc
	v_div_scale_f32 v161, s[4:5], v153, v153, 1.0
	v_rcp_f32_e32 v162, v161
	v_div_scale_f32 v163, vcc, 1.0, v153, 1.0
	v_fma_f32 v164, -v161, v162, 1.0
	v_fmac_f32_e32 v162, v164, v162
	v_mul_f32_e32 v164, v163, v162
	v_fma_f32 v165, -v161, v164, v163
	v_fmac_f32_e32 v164, v165, v162
	v_fma_f32 v161, -v161, v164, v163
	v_div_fmas_f32 v161, v161, v162, v164
	v_div_fixup_f32 v153, v161, v153, 1.0
	v_mul_f32_e32 v162, 0x3e0293ee, v153
	v_pk_mul_f32 v[128:129], v[128:129], v[162:163] op_sel_hi:[1,0]
	v_pk_mul_f32 v[126:127], v[126:127], v[162:163] op_sel_hi:[1,0]
	v_pk_mul_f32 v[124:125], v[124:125], v[162:163] op_sel_hi:[1,0]
	v_pk_mul_f32 v[122:123], v[122:123], v[162:163] op_sel_hi:[1,0]
	v_pk_mul_f32 v[120:121], v[120:121], v[162:163] op_sel_hi:[1,0]
	v_pk_mul_f32 v[118:119], v[118:119], v[162:163] op_sel_hi:[1,0]
	v_pk_mul_f32 v[164:165], v[116:117], v[162:163] op_sel_hi:[1,0]
	v_pk_mul_f32 v[162:163], v[114:115], v[162:163] op_sel_hi:[1,0]
	v_cvt_pk_bf16_f32 v114, v126, v127
	v_cvt_pk_bf16_f32 v115, v128, v129
	v_cvt_pk_bf16_f32 v116, v122, v123
	v_cvt_pk_bf16_f32 v117, v124, v125
	global_store_dwordx4 v[146:147], v[114:117], off
	s_nop 1
	v_cvt_pk_bf16_f32 v114, v118, v119
	v_cvt_pk_bf16_f32 v115, v120, v121
	v_cvt_pk_bf16_f32 v116, v162, v163
	v_cvt_pk_bf16_f32 v117, v164, v165
	global_store_dwordx4 v[146:147], v[114:117], off offset:256
	s_nop 1
	v_mov_b32_e32 v115, v170
	s_nop 0
	v_or_b32_e32 v114, 16, v152
	v_fmamk_f32 v115, v115, 0x3a000000, v159
	v_mul_f32_e32 v116, 0x4f800000, v115
	v_cmp_gt_f32_e32 vcc, s83, v115
	s_nop 1
	v_cndmask_b32_e32 v116, v115, v116, vcc
	v_sqrt_f32_e32 v117, v116
	v_ashrrev_i32_e32 v115, 31, v114
	v_lshlrev_b64 v[114:115], 10, v[114:115]
	v_lshl_add_u64 v[114:115], s[6:7], 0, v[114:115]
	v_add_u32_e32 v118, -1, v117
	v_add_u32_e32 v119, 1, v117
	v_fma_f32 v120, -v118, v117, v116
	v_fma_f32 v121, -v119, v117, v116
	v_cmp_ge_f32_e64 s[4:5], 0, v120
	v_lshl_add_u64 v[114:115], v[114:115], 0, v[150:151]
	s_nop 0
	v_cndmask_b32_e64 v117, v117, v118, s[4:5]
	v_cmp_lt_f32_e64 s[4:5], 0, v121
	s_nop 1
	v_cndmask_b32_e64 v117, v117, v119, s[4:5]
	v_mul_f32_e32 v118, 0x37800000, v117
	v_cndmask_b32_e32 v117, v117, v118, vcc
	v_cmp_class_f32_e32 vcc, v116, v160
	s_nop 1
	v_cndmask_b32_e32 v116, v117, v116, vcc
	v_div_scale_f32 v117, s[4:5], v116, v116, 1.0
	v_rcp_f32_e32 v118, v117
	v_div_scale_f32 v119, vcc, 1.0, v116, 1.0
	v_fma_f32 v120, -v117, v118, 1.0
	v_fmac_f32_e32 v118, v120, v118
	v_mul_f32_e32 v120, v119, v118
	v_fma_f32 v121, -v117, v120, v119
	v_fmac_f32_e32 v120, v121, v118
	v_fma_f32 v117, -v117, v120, v119
	v_div_fmas_f32 v117, v117, v118, v120
	v_div_fixup_f32 v116, v117, v116, 1.0
	v_mul_f32_e32 v116, 0x3e0293ee, v116
	v_pk_mul_f32 v[112:113], v[112:113], v[116:117] op_sel_hi:[1,0]
	v_pk_mul_f32 v[110:111], v[110:111], v[116:117] op_sel_hi:[1,0]
	v_pk_mul_f32 v[108:109], v[108:109], v[116:117] op_sel_hi:[1,0]
	v_pk_mul_f32 v[106:107], v[106:107], v[116:117] op_sel_hi:[1,0]
	v_pk_mul_f32 v[104:105], v[104:105], v[116:117] op_sel_hi:[1,0]
	v_pk_mul_f32 v[102:103], v[102:103], v[116:117] op_sel_hi:[1,0]
	v_pk_mul_f32 v[118:119], v[100:101], v[116:117] op_sel_hi:[1,0]
	v_pk_mul_f32 v[116:117], v[98:99], v[116:117] op_sel_hi:[1,0]
	v_cvt_pk_bf16_f32 v98, v110, v111
	v_cvt_pk_bf16_f32 v99, v112, v113
	v_cvt_pk_bf16_f32 v100, v106, v107
	v_cvt_pk_bf16_f32 v101, v108, v109
	global_store_dwordx4 v[114:115], v[98:101], off
	s_nop 1
	v_cvt_pk_bf16_f32 v98, v102, v103
	v_cvt_pk_bf16_f32 v99, v104, v105
	v_cvt_pk_bf16_f32 v100, v116, v117
	v_cvt_pk_bf16_f32 v101, v118, v119
	global_store_dwordx4 v[114:115], v[98:101], off offset:256
	s_nop 1
	v_mov_b32_e32 v99, v171
	s_nop 0
	v_or_b32_e32 v98, 32, v152
	v_fmamk_f32 v99, v99, 0x3a000000, v159
	v_mul_f32_e32 v100, 0x4f800000, v99
	v_cmp_gt_f32_e32 vcc, s83, v99
	s_nop 1
	v_cndmask_b32_e32 v100, v99, v100, vcc
	v_sqrt_f32_e32 v101, v100
	v_ashrrev_i32_e32 v99, 31, v98
	v_lshlrev_b64 v[98:99], 10, v[98:99]
	v_lshl_add_u64 v[98:99], s[6:7], 0, v[98:99]
	v_add_u32_e32 v102, -1, v101
	v_add_u32_e32 v103, 1, v101
	v_fma_f32 v104, -v102, v101, v100
	v_fma_f32 v105, -v103, v101, v100
	v_cmp_ge_f32_e64 s[4:5], 0, v104
; __device__ __forceinline__ void st8(bf16_t* p, const f32x4& a, const f32x4& b) { u32x4 w; w.x = pk2(a[0], a[1]); w.y = pk2(a[2], a[3]); w.z = pk2(b[0], b[1]); w.w = pk2(b[2], b[3]); *(u32x4*)p = w; }
;     __device__ __forceinline__ void operator()(const f32x4 (&acc)[2][2][4][2], const Unit& u, int wr, int wc, int fr, int fq) const {
;         const int row0 = u.pm * 256 + wr * 64 + fr, col0 = u.pn * 256 + wc * 32 + 8 * fq;
; #pragma unroll
;         for (int ai = 0; ai < 2; ++ai)
; #pragma unroll
;             for (int m = 0; m < 4; ++m) {
;                 const int row = row0 + ai * 128 + m * 16; const float rs = sc * (1.0f / sqrtf(ssq[row] * (1.f / D) + RMS_EPS));
;                 bf16_t* rp = O + (size_t)row * ldc + col0;
; #pragma unroll
;                 for (int bj = 0; bj < 2; ++bj) st8(rp + bj * 128, acc[ai][bj][m][0] * rs, acc[ai][bj][m][1] * rs);
;             }
;     }
	v_lshl_add_u64 v[98:99], v[98:99], 0, v[150:151]
	s_nop 0
	v_cndmask_b32_e64 v101, v101, v102, s[4:5]
	v_cmp_lt_f32_e64 s[4:5], 0, v105
	s_nop 1
	v_cndmask_b32_e64 v101, v101, v103, s[4:5]
	v_mul_f32_e32 v102, 0x37800000, v101
	v_cndmask_b32_e32 v101, v101, v102, vcc
	v_cmp_class_f32_e32 vcc, v100, v160
	s_nop 1
	v_cndmask_b32_e32 v100, v101, v100, vcc
	v_div_scale_f32 v101, s[4:5], v100, v100, 1.0
	v_rcp_f32_e32 v102, v101
	v_div_scale_f32 v103, vcc, 1.0, v100, 1.0
	v_fma_f32 v104, -v101, v102, 1.0
	v_fmac_f32_e32 v102, v104, v102
	v_mul_f32_e32 v104, v103, v102
	v_fma_f32 v105, -v101, v104, v103
	v_fmac_f32_e32 v104, v105, v102
	v_fma_f32 v101, -v101, v104, v103
	v_div_fmas_f32 v101, v101, v102, v104
	v_div_fixup_f32 v100, v101, v100, 1.0
	v_mul_f32_e32 v100, 0x3e0293ee, v100
	v_pk_mul_f32 v[96:97], v[96:97], v[100:101] op_sel_hi:[1,0]
	v_pk_mul_f32 v[94:95], v[94:95], v[100:101] op_sel_hi:[1,0]
	v_pk_mul_f32 v[92:93], v[92:93], v[100:101] op_sel_hi:[1,0]
	v_pk_mul_f32 v[90:91], v[90:91], v[100:101] op_sel_hi:[1,0]
	v_pk_mul_f32 v[88:89], v[88:89], v[100:101] op_sel_hi:[1,0]
	v_pk_mul_f32 v[86:87], v[86:87], v[100:101] op_sel_hi:[1,0]
	v_pk_mul_f32 v[102:103], v[84:85], v[100:101] op_sel_hi:[1,0]
	v_pk_mul_f32 v[100:101], v[82:83], v[100:101] op_sel_hi:[1,0]
	v_cvt_pk_bf16_f32 v82, v94, v95
	v_cvt_pk_bf16_f32 v83, v96, v97
	v_cvt_pk_bf16_f32 v84, v90, v91
	v_cvt_pk_bf16_f32 v85, v92, v93
	global_store_dwordx4 v[98:99], v[82:85], off
	s_nop 1
	v_cvt_pk_bf16_f32 v82, v86, v87
	v_cvt_pk_bf16_f32 v83, v88, v89
	v_cvt_pk_bf16_f32 v84, v100, v101
	v_cvt_pk_bf16_f32 v85, v102, v103
	global_store_dwordx4 v[98:99], v[82:85], off offset:256
	s_nop 1
	v_mov_b32_e32 v83, v172
	s_nop 0
	v_or_b32_e32 v82, 48, v152
	v_fmamk_f32 v83, v83, 0x3a000000, v159
	v_mul_f32_e32 v84, 0x4f800000, v83
	v_cmp_gt_f32_e32 vcc, s83, v83
	s_nop 1
	v_cndmask_b32_e32 v84, v83, v84, vcc
	v_sqrt_f32_e32 v85, v84
	v_ashrrev_i32_e32 v83, 31, v82
	v_lshlrev_b64 v[82:83], 10, v[82:83]
	v_lshl_add_u64 v[82:83], s[6:7], 0, v[82:83]
	v_add_u32_e32 v86, -1, v85
	v_add_u32_e32 v87, 1, v85
	v_fma_f32 v88, -v86, v85, v84
	v_fma_f32 v89, -v87, v85, v84
	v_cmp_ge_f32_e64 s[4:5], 0, v88
	v_lshl_add_u64 v[82:83], v[82:83], 0, v[150:151]
	s_nop 0
	v_cndmask_b32_e64 v85, v85, v86, s[4:5]
	v_cmp_lt_f32_e64 s[4:5], 0, v89
	s_nop 1
	v_cndmask_b32_e64 v85, v85, v87, s[4:5]
	v_mul_f32_e32 v86, 0x37800000, v85
	v_cndmask_b32_e32 v85, v85, v86, vcc
	v_cmp_class_f32_e32 vcc, v84, v160
	s_nop 1
	v_cndmask_b32_e32 v84, v85, v84, vcc
	v_div_scale_f32 v85, s[4:5], v84, v84, 1.0
	v_rcp_f32_e32 v86, v85
	v_div_scale_f32 v87, vcc, 1.0, v84, 1.0
	s_mov_b64 s[4:5], 0x20000
	v_fma_f32 v88, -v85, v86, 1.0
	v_fmac_f32_e32 v86, v88, v86
	v_mul_f32_e32 v88, v87, v86
	v_fma_f32 v89, -v85, v88, v87
	v_fmac_f32_e32 v88, v89, v86
	v_fma_f32 v85, -v85, v88, v87
	v_div_fmas_f32 v85, v85, v86, v88
	v_div_fixup_f32 v84, v85, v84, 1.0
	v_mul_f32_e32 v84, 0x3e0293ee, v84
	v_pk_mul_f32 v[80:81], v[80:81], v[84:85] op_sel_hi:[1,0]
	v_pk_mul_f32 v[78:79], v[78:79], v[84:85] op_sel_hi:[1,0]
	v_pk_mul_f32 v[76:77], v[76:77], v[84:85] op_sel_hi:[1,0]
	v_pk_mul_f32 v[74:75], v[74:75], v[84:85] op_sel_hi:[1,0]
	v_pk_mul_f32 v[72:73], v[72:73], v[84:85] op_sel_hi:[1,0]
	v_pk_mul_f32 v[70:71], v[70:71], v[84:85] op_sel_hi:[1,0]
	v_pk_mul_f32 v[86:87], v[68:69], v[84:85] op_sel_hi:[1,0]
	v_pk_mul_f32 v[84:85], v[66:67], v[84:85] op_sel_hi:[1,0]
	v_cvt_pk_bf16_f32 v66, v78, v79
	v_cvt_pk_bf16_f32 v67, v80, v81
	v_cvt_pk_bf16_f32 v68, v74, v75
	v_cvt_pk_bf16_f32 v69, v76, v77
	global_store_dwordx4 v[82:83], v[66:69], off
	s_nop 1
	v_cvt_pk_bf16_f32 v66, v70, v71
	v_cvt_pk_bf16_f32 v67, v72, v73
	v_cvt_pk_bf16_f32 v68, v84, v85
	v_cvt_pk_bf16_f32 v69, v86, v87
	global_store_dwordx4 v[82:83], v[66:69], off offset:256
	s_nop 1
	v_mov_b32_e32 v66, v173
	v_fmamk_f32 v66, v66, 0x3a000000, v159
	v_mul_f32_e32 v67, 0x4f800000, v66
	v_cmp_gt_f32_e32 vcc, s83, v66
	s_nop 1
	v_cndmask_b32_e32 v68, v66, v67, vcc
	v_sqrt_f32_e32 v69, v68
	v_lshl_add_u64 v[66:67], v[146:147], 0, s[4:5]
	v_add_u32_e32 v70, -1, v69
	v_add_u32_e32 v71, 1, v69
	v_fma_f32 v72, -v70, v69, v68
	v_fma_f32 v73, -v71, v69, v68
	v_cmp_ge_f32_e64 s[4:5], 0, v72
	s_nop 1
	v_cndmask_b32_e64 v69, v69, v70, s[4:5]
	v_cmp_lt_f32_e64 s[4:5], 0, v73
	s_nop 1
	v_cndmask_b32_e64 v69, v69, v71, s[4:5]
	v_mul_f32_e32 v70, 0x37800000, v69
	v_cndmask_b32_e32 v69, v69, v70, vcc
	v_cmp_class_f32_e32 vcc, v68, v160
	s_nop 1
	v_cndmask_b32_e32 v70, v69, v68, vcc
	v_div_scale_f32 v71, s[4:5], v70, v70, 1.0
	v_rcp_f32_e32 v72, v71
	v_add_co_u32_e32 v68, vcc, s24, v146
	s_mov_b64 s[4:5], 0x24000
	s_nop 0
	v_addc_co_u32_e32 v69, vcc, 0, v147, vcc
	v_fma_f32 v74, -v71, v72, 1.0
	v_div_scale_f32 v73, vcc, 1.0, v70, 1.0
	v_fmac_f32_e32 v72, v74, v72
	v_mul_f32_e32 v74, v73, v72
	v_fma_f32 v75, -v71, v74, v73
	v_fmac_f32_e32 v74, v75, v72
	v_fma_f32 v71, -v71, v74, v73
	v_div_fmas_f32 v71, v71, v72, v74
	v_div_fixup_f32 v70, v71, v70, 1.0
	v_mul_f32_e32 v70, 0x3e0293ee, v70
	v_pk_mul_f32 v[64:65], v[64:65], v[70:71] op_sel_hi:[1,0]
	v_pk_mul_f32 v[62:63], v[62:63], v[70:71] op_sel_hi:[1,0]
	v_pk_mul_f32 v[60:61], v[60:61], v[70:71] op_sel_hi:[1,0]
	v_pk_mul_f32 v[58:59], v[58:59], v[70:71] op_sel_hi:[1,0]
	v_pk_mul_f32 v[56:57], v[56:57], v[70:71] op_sel_hi:[1,0]
	v_pk_mul_f32 v[54:55], v[54:55], v[70:71] op_sel_hi:[1,0]
	v_pk_mul_f32 v[72:73], v[52:53], v[70:71] op_sel_hi:[1,0]
	v_pk_mul_f32 v[70:71], v[50:51], v[70:71] op_sel_hi:[1,0]
	v_cvt_pk_bf16_f32 v50, v62, v63
	v_cvt_pk_bf16_f32 v51, v64, v65
	v_cvt_pk_bf16_f32 v52, v58, v59
	v_cvt_pk_bf16_f32 v53, v60, v61
	global_store_dwordx4 v[68:69], v[50:53], off
; __device__ __forceinline__ void st8(bf16_t* p, const f32x4& a, const f32x4& b) { u32x4 w; w.x = pk2(a[0], a[1]); w.y = pk2(a[2], a[3]); w.z = pk2(b[0], b[1]); w.w = pk2(b[2], b[3]); *(u32x4*)p = w; }
;     __device__ __forceinline__ void operator()(const f32x4 (&acc)[2][2][4][2], const Unit& u, int wr, int wc, int fr, int fq) const {
;         const int row0 = u.pm * 256 + wr * 64 + fr, col0 = u.pn * 256 + wc * 32 + 8 * fq;
; #pragma unroll
;         for (int ai = 0; ai < 2; ++ai)
; #pragma unroll
;             for (int m = 0; m < 4; ++m) {
;                 const int row = row0 + ai * 128 + m * 16; const float rs = sc * (1.0f / sqrtf(ssq[row] * (1.f / D) + RMS_EPS));
;                 bf16_t* rp = O + (size_t)row * ldc + col0;
; #pragma unroll
;                 for (int bj = 0; bj < 2; ++bj) st8(rp + bj * 128, acc[ai][bj][m][0] * rs, acc[ai][bj][m][1] * rs);
;             }
;     }
	s_mov_b32 s24, 0x24000
	s_nop 0
	v_cvt_pk_bf16_f32 v50, v54, v55
	v_cvt_pk_bf16_f32 v51, v56, v57
	v_cvt_pk_bf16_f32 v52, v70, v71
	v_cvt_pk_bf16_f32 v53, v72, v73
	global_store_dwordx4 v[66:67], v[50:53], off offset:256
	s_nop 1
	v_mov_b32_e32 v50, v174
	v_fmamk_f32 v50, v50, 0x3a000000, v159
	v_mul_f32_e32 v51, 0x4f800000, v50
	v_cmp_gt_f32_e32 vcc, s83, v50
	s_nop 1
	v_cndmask_b32_e32 v52, v50, v51, vcc
	v_sqrt_f32_e32 v53, v52
	v_lshl_add_u64 v[50:51], v[146:147], 0, s[4:5]
	v_add_u32_e32 v54, -1, v53
	v_add_u32_e32 v55, 1, v53
	v_fma_f32 v56, -v54, v53, v52
	v_fma_f32 v57, -v55, v53, v52
	v_cmp_ge_f32_e64 s[4:5], 0, v56
	s_nop 1
	v_cndmask_b32_e64 v53, v53, v54, s[4:5]
	v_cmp_lt_f32_e64 s[4:5], 0, v57
	s_nop 1
	v_cndmask_b32_e64 v53, v53, v55, s[4:5]
	v_mul_f32_e32 v54, 0x37800000, v53
	v_cndmask_b32_e32 v53, v53, v54, vcc
	v_cmp_class_f32_e32 vcc, v52, v160
	s_nop 1
	v_cndmask_b32_e32 v54, v53, v52, vcc
	v_div_scale_f32 v55, s[4:5], v54, v54, 1.0
	v_rcp_f32_e32 v56, v55
	v_add_co_u32_e32 v52, vcc, s24, v146
	s_mov_b64 s[4:5], 0x28000
	s_nop 0
	v_addc_co_u32_e32 v53, vcc, 0, v147, vcc
	v_fma_f32 v58, -v55, v56, 1.0
	v_div_scale_f32 v57, vcc, 1.0, v54, 1.0
	v_fmac_f32_e32 v56, v58, v56
	v_mul_f32_e32 v58, v57, v56
	v_fma_f32 v59, -v55, v58, v57
	v_fmac_f32_e32 v58, v59, v56
	v_fma_f32 v55, -v55, v58, v57
	v_div_fmas_f32 v55, v55, v56, v58
	v_div_fixup_f32 v54, v55, v54, 1.0
	v_mul_f32_e32 v54, 0x3e0293ee, v54
	v_pk_mul_f32 v[48:49], v[48:49], v[54:55] op_sel_hi:[1,0]
	v_pk_mul_f32 v[46:47], v[46:47], v[54:55] op_sel_hi:[1,0]
	v_pk_mul_f32 v[44:45], v[44:45], v[54:55] op_sel_hi:[1,0]
	v_pk_mul_f32 v[42:43], v[42:43], v[54:55] op_sel_hi:[1,0]
	v_pk_mul_f32 v[40:41], v[40:41], v[54:55] op_sel_hi:[1,0]
	v_pk_mul_f32 v[38:39], v[38:39], v[54:55] op_sel_hi:[1,0]
	v_pk_mul_f32 v[56:57], v[36:37], v[54:55] op_sel_hi:[1,0]
	v_pk_mul_f32 v[54:55], v[34:35], v[54:55] op_sel_hi:[1,0]
	v_cvt_pk_bf16_f32 v34, v46, v47
	v_cvt_pk_bf16_f32 v35, v48, v49
	v_cvt_pk_bf16_f32 v36, v42, v43
	v_cvt_pk_bf16_f32 v37, v44, v45
	global_store_dwordx4 v[52:53], v[34:37], off
	s_nop 1
	v_cvt_pk_bf16_f32 v34, v38, v39
	v_cvt_pk_bf16_f32 v35, v40, v41
	v_cvt_pk_bf16_f32 v36, v54, v55
	v_cvt_pk_bf16_f32 v37, v56, v57
	global_store_dwordx4 v[50:51], v[34:37], off offset:256
	s_nop 1
	v_mov_b32_e32 v34, v175
	v_fmamk_f32 v34, v34, 0x3a000000, v159
	v_mul_f32_e32 v35, 0x4f800000, v34
	v_cmp_gt_f32_e32 vcc, s83, v34
	s_nop 1
	v_cndmask_b32_e32 v36, v34, v35, vcc
	v_sqrt_f32_e32 v37, v36
	v_lshl_add_u64 v[34:35], v[146:147], 0, s[4:5]
	v_add_u32_e32 v38, -1, v37
	v_add_u32_e32 v39, 1, v37
	v_fma_f32 v40, -v38, v37, v36
	v_fma_f32 v41, -v39, v37, v36
	v_cmp_ge_f32_e64 s[4:5], 0, v40
	s_nop 1
	v_cndmask_b32_e64 v37, v37, v38, s[4:5]
	v_cmp_lt_f32_e64 s[4:5], 0, v41
	s_nop 1
	v_cndmask_b32_e64 v37, v37, v39, s[4:5]
	v_mul_f32_e32 v38, 0x37800000, v37
	v_cndmask_b32_e32 v37, v37, v38, vcc
	v_cmp_class_f32_e32 vcc, v36, v160
	s_nop 1
	v_cndmask_b32_e32 v38, v37, v36, vcc
	v_div_scale_f32 v39, s[4:5], v38, v38, 1.0
	v_rcp_f32_e32 v40, v39
	v_add_co_u32_e32 v36, vcc, s84, v146
	v_fma_f32 v42, -v39, v40, 1.0
	s_nop 0
	v_addc_co_u32_e32 v37, vcc, 0, v147, vcc
	v_div_scale_f32 v41, vcc, 1.0, v38, 1.0
	v_fmac_f32_e32 v40, v42, v40
	v_mul_f32_e32 v42, v41, v40
	v_fma_f32 v43, -v39, v42, v41
	v_fmac_f32_e32 v42, v43, v40
	v_fma_f32 v39, -v39, v42, v41
	v_div_fmas_f32 v39, v39, v40, v42
	v_div_fixup_f32 v38, v39, v38, 1.0
	v_mul_f32_e32 v38, 0x3e0293ee, v38
	v_pk_mul_f32 v[32:33], v[32:33], v[38:39] op_sel_hi:[1,0]
	v_pk_mul_f32 v[30:31], v[30:31], v[38:39] op_sel_hi:[1,0]
	v_pk_mul_f32 v[28:29], v[28:29], v[38:39] op_sel_hi:[1,0]
	v_pk_mul_f32 v[26:27], v[26:27], v[38:39] op_sel_hi:[1,0]
	v_pk_mul_f32 v[24:25], v[24:25], v[38:39] op_sel_hi:[1,0]
	v_pk_mul_f32 v[22:23], v[22:23], v[38:39] op_sel_hi:[1,0]
	v_pk_mul_f32 v[40:41], v[20:21], v[38:39] op_sel_hi:[1,0]
	v_pk_mul_f32 v[38:39], v[18:19], v[38:39] op_sel_hi:[1,0]
	v_cvt_pk_bf16_f32 v18, v30, v31
	v_cvt_pk_bf16_f32 v19, v32, v33
	v_cvt_pk_bf16_f32 v20, v26, v27
	v_cvt_pk_bf16_f32 v21, v28, v29
	global_store_dwordx4 v[36:37], v[18:21], off
	s_nop 1
	v_cvt_pk_bf16_f32 v18, v22, v23
	v_cvt_pk_bf16_f32 v19, v24, v25
	v_cvt_pk_bf16_f32 v20, v38, v39
	v_cvt_pk_bf16_f32 v21, v40, v41
	global_store_dwordx4 v[34:35], v[18:21], off offset:256
	s_nop 1
	v_mov_b32_e32 v18, v176
	v_fmamk_f32 v18, v18, 0x3a000000, v159
	v_mul_f32_e32 v19, 0x4f800000, v18
	v_cmp_gt_f32_e32 vcc, s83, v18
	s_nop 1
	v_cndmask_b32_e32 v20, v18, v19, vcc
	v_sqrt_f32_e32 v21, v20
	v_lshl_add_u64 v[18:19], v[146:147], 0, s[58:59]
	v_add_u32_e32 v22, -1, v21
	v_add_u32_e32 v23, 1, v21
	v_fma_f32 v24, -v22, v21, v20
	v_fma_f32 v25, -v23, v21, v20
	v_cmp_ge_f32_e64 s[4:5], 0, v24
	s_nop 1
	v_cndmask_b32_e64 v21, v21, v22, s[4:5]
	v_cmp_lt_f32_e64 s[4:5], 0, v25
	s_nop 1
	v_cndmask_b32_e64 v21, v21, v23, s[4:5]
	v_mul_f32_e32 v22, 0x37800000, v21
	v_cndmask_b32_e32 v21, v21, v22, vcc
	v_cmp_class_f32_e32 vcc, v20, v160
	s_nop 1
	v_cndmask_b32_e32 v22, v21, v20, vcc
	v_div_scale_f32 v23, s[4:5], v22, v22, 1.0
	v_rcp_f32_e32 v24, v23
	v_add_co_u32_e32 v20, vcc, s85, v146
	v_fma_f32 v26, -v23, v24, 1.0
	s_nop 0
	v_addc_co_u32_e32 v21, vcc, 0, v147, vcc
	v_div_scale_f32 v25, vcc, 1.0, v22, 1.0
	v_fmac_f32_e32 v24, v26, v24
	v_mul_f32_e32 v26, v25, v24
	v_fma_f32 v27, -v23, v26, v25
	v_fmac_f32_e32 v26, v27, v24
	v_fma_f32 v23, -v23, v26, v25
	v_div_fmas_f32 v23, v23, v24, v26
	v_div_fixup_f32 v22, v23, v22, 1.0
	v_mul_f32_e32 v22, 0x3e0293ee, v22
	s_andn2_b64 vcc, exec, s[2:3]
	v_pk_mul_f32 v[16:17], v[16:17], v[22:23] op_sel_hi:[1,0]
	v_pk_mul_f32 v[14:15], v[14:15], v[22:23] op_sel_hi:[1,0]
	v_pk_mul_f32 v[12:13], v[12:13], v[22:23] op_sel_hi:[1,0]
	v_pk_mul_f32 v[10:11], v[10:11], v[22:23] op_sel_hi:[1,0]
	v_pk_mul_f32 v[8:9], v[8:9], v[22:23] op_sel_hi:[1,0]
	v_pk_mul_f32 v[6:7], v[6:7], v[22:23] op_sel_hi:[1,0]
	v_pk_mul_f32 v[24:25], v[4:5], v[22:23] op_sel_hi:[1,0]
	v_pk_mul_f32 v[22:23], v[2:3], v[22:23] op_sel_hi:[1,0]
	v_cvt_pk_bf16_f32 v2, v14, v15
	v_cvt_pk_bf16_f32 v3, v16, v17
	v_cvt_pk_bf16_f32 v4, v10, v11
	v_cvt_pk_bf16_f32 v5, v12, v13
	s_mov_b64 s[2:3], -1
	global_store_dwordx4 v[20:21], v[2:5], off
	s_nop 1
	v_cvt_pk_bf16_f32 v2, v6, v7
	v_cvt_pk_bf16_f32 v3, v8, v9
	v_cvt_pk_bf16_f32 v4, v22, v23
	v_cvt_pk_bf16_f32 v5, v24, v25
	global_store_dwordx4 v[18:19], v[2:5], off offset:256
	s_cbranch_vccnz .LBB0_726
	s_andn2_b64 vcc, exec, s[52:53]
	s_cbranch_vccnz .LBB0_725
	s_barrier
	s_branch .LBB0_725

; #define LAS __attribute__((address_space(3)))
;     ...
;             const LAS unsigned char* kb_ = lds + ATT_KB + b * 16384;
;             const LAS unsigned char* vb_ = lds + ATT_VB + b * 16384;
;             f32x16 st[2];
;             bf16x8 ka[8];
; #pragma unroll
;             for (int ks = 0; ks < 8; ++ks) ka[ks] = *(const LAS bf16x8*)(kb_ + (kbase ^ (unsigned)(ks << 5)));
;             bf16x8 va[2][4];
; #pragma unroll
;             for (int dt = 0; dt < 4; ++dt) va[0][dt] = *(const LAS bf16x8*)(vb_ + dt * 4096 + vbase);
; #pragma unroll
;             for (int rt = 0; rt < 2; ++rt)
; #pragma unroll
;                 for (int r = 0; r < 16; ++r) st[rt][r] = 0.f;
;             __builtin_amdgcn_sched_barrier(0);
;             __builtin_amdgcn_s_setprio(1);
; #pragma unroll
;             for (int ks = 0; ks < 8; ++ks) { st[0] = __builtin_amdgcn_mfma_f32_32x32x16_bf16(ka[ks], qf[ks], st[0], 0, 0, 0);
;                 ka[ks] = *(const LAS bf16x8*)(kb_ + 8192 + (kbase ^ (unsigned)(ks << 5))); __builtin_amdgcn_sched_barrier(0); }
; #pragma unroll
;             for (int ks = 0; ks < 8; ++ks) st[1] = __builtin_amdgcn_mfma_f32_32x32x16_bf16(ka[ks], qf[ks], st[1], 0, 0, 0);
;             __builtin_amdgcn_s_setprio(0);
;             if (MOBA) {
;                 if (own && 64 * kt + 63 > 32 * w) {
;                     const int qloc = 32 * w + ql;
; #pragma unroll
;                     for (int rt = 0; rt < 2; ++rt)
; #pragma unroll
;                         for (int r = 0; r < 16; ++r) { const int key = 64 * kt + 32 * rt + 16 * (r >> 3) + 8 * h2 + (r & 7); if (key > qloc) st[rt][r] = NEGBIG; }
;                 }
;             }
;             float mx = st[0][0];
; #pragma unroll
;             for (int rt = 0; rt < 2; ++rt)
; #pragma unroll
;                 for (int r = 0; r < 16; ++r) mx = fmaxf(mx, st[rt][r]);
;             if (MOBA) mx = selme ? mx : NEGBIG;
;             mx = fmaxf(mx, __shfl_xor(mx, 32));
;             if (__builtin_amdgcn_ballot_w64(mx > mrow + 8.0f) != 0ull) {
;                 const float mnew = fmaxf(mrow, mx), alpha = __builtin_amdgcn_exp2f(mrow - mnew);
;                 mrow = mnew; lsum *= alpha;
; #pragma unroll
;                 for (int dt = 0; dt < 4; ++dt)
; #pragma unroll
;                     for (int r = 0; r < 16; ++r) ot[dt][r] *= alpha;
;             }
.LBB0_838:
	s_cmp_eq_u64 exec, 0
	s_cbranch_scc1 .LBB0_842
	s_lshl_b32 s24, s4, 14
	s_add_i32 s44, s24, 0
	v_add_u32_e32 v16, s44, v160
	v_add_u32_e32 v173, s44, v163
	v_add_u32_e32 v206, s44, v165
	v_add_u32_e32 v211, s44, v167
	v_add_u32_e32 v4, s44, v161
	v_add_u32_e32 v17, s44, v162
	ds_read_b128 v[82:85], v16
	ds_read_b128 v[86:89], v17
	v_add_u32_e32 v202, s44, v164
	ds_read_b128 v[90:93], v173
	ds_read_b128 v[94:97], v202
	v_add_u32_e32 v210, s44, v166
	ds_read_b128 v[174:177], v206
	ds_read_b128 v[178:181], v210
	v_add_u32_e32 v212, s44, v168
	ds_read_b128 v[182:185], v211
	ds_read_b128 v[186:189], v212
	ds_read_b128 v[146:149], v4 offset:49152
	ds_read_b128 v[12:15], v4 offset:53248
	ds_read_b128 v[8:11], v4 offset:57344
	ds_read_b128 v[4:7], v4 offset:61440
	s_setprio 1
	s_waitcnt lgkmcnt(11)
	v_mfma_f32_32x32x16_bf16 v[98:113], v[82:85], v[114:117], 0
	ds_read_b128 v[190:193], v16 offset:8192
	s_waitcnt lgkmcnt(11)
	v_mfma_f32_32x32x16_bf16 v[98:113], v[86:89], v[118:121], v[98:113]
	ds_read_b128 v[194:197], v17 offset:8192
	s_waitcnt lgkmcnt(11)
	v_mfma_f32_32x32x16_bf16 v[98:113], v[90:93], v[122:125], v[98:113]
	ds_read_b128 v[198:201], v173 offset:8192
	s_waitcnt lgkmcnt(11)
	v_mfma_f32_32x32x16_bf16 v[98:113], v[94:97], v[126:129], v[98:113]
	ds_read_b128 v[202:205], v202 offset:8192
	s_waitcnt lgkmcnt(11)
	v_mfma_f32_32x32x16_bf16 v[98:113], v[174:177], v[130:133], v[98:113]
	ds_read_b128 v[206:209], v206 offset:8192
	s_waitcnt lgkmcnt(11)
	v_mfma_f32_32x32x16_bf16 v[98:113], v[178:181], v[134:137], v[98:113]
	ds_read_b128 v[174:177], v210 offset:8192
	s_waitcnt lgkmcnt(11)
	v_mfma_f32_32x32x16_bf16 v[98:113], v[182:185], v[138:141], v[98:113]
	ds_read_b128 v[178:181], v211 offset:8192
	s_waitcnt lgkmcnt(11)
	v_mfma_f32_32x32x16_bf16 v[98:113], v[186:189], v[142:145], v[98:113]
	ds_read_b128 v[182:185], v212 offset:8192
	s_waitcnt lgkmcnt(7)
	v_mfma_f32_32x32x16_bf16 v[82:97], v[190:193], v[114:117], 0
	s_waitcnt lgkmcnt(6)
	v_mfma_f32_32x32x16_bf16 v[82:97], v[194:197], v[118:121], v[82:97]
	s_waitcnt lgkmcnt(5)
	v_mfma_f32_32x32x16_bf16 v[82:97], v[198:201], v[122:125], v[82:97]
	s_waitcnt lgkmcnt(4)
	v_mfma_f32_32x32x16_bf16 v[82:97], v[202:205], v[126:129], v[82:97]
	s_waitcnt lgkmcnt(3)
	v_mfma_f32_32x32x16_bf16 v[82:97], v[206:209], v[130:133], v[82:97]
	s_waitcnt lgkmcnt(2)
	v_mfma_f32_32x32x16_bf16 v[82:97], v[174:177], v[134:137], v[82:97]
	s_waitcnt lgkmcnt(1)
	v_mfma_f32_32x32x16_bf16 v[82:97], v[178:181], v[138:141], v[82:97]
	s_waitcnt lgkmcnt(0)
	v_mfma_f32_32x32x16_bf16 v[82:97], v[182:185], v[142:145], v[82:97]
	s_setprio 0
	s_nop 0
	v_max_f32_e32 v16, v99, v99
	v_max_f32_e32 v17, v98, v98
	v_max_f32_e32 v16, v17, v16
	v_max3_f32 v16, v16, v100, v101
	v_max3_f32 v16, v16, v102, v103
	v_max3_f32 v16, v16, v104, v105
	v_max3_f32 v16, v16, v106, v107
	v_max3_f32 v16, v16, v108, v109
	v_max3_f32 v16, v16, v110, v111
	v_max3_f32 v16, v16, v112, v113
	v_max3_f32 v16, v16, v82, v83
	v_max3_f32 v16, v16, v84, v85
	v_max3_f32 v16, v16, v86, v87
	v_max3_f32 v16, v16, v88, v89
	v_and_b32_e32 v173, 64, v1
	v_max3_f32 v16, v16, v90, v91
	v_xor_b32_e32 v17, 32, v1
	v_add_u32_e32 v173, 64, v173
	v_max3_f32 v16, v16, v92, v93
	v_cmp_lt_i32_e32 vcc, v17, v173
	v_max3_f32 v16, v16, v94, v95
	v_max3_f32 v16, v16, v96, v97
	v_cndmask_b32_e32 v17, v1, v17, vcc
	v_lshlrev_b32_e32 v17, 2, v17
	v_mov_b32_e32 v17, v16
	s_nop 1
	v_permlane32_swap_b32_e32 v17, v16
	v_max_f32_e32 v17, v17, v17
	v_max_f32_e32 v16, v16, v17
	v_add_f32_e32 v17, 0x41000000, v172
	v_cmp_gt_f32_e32 vcc, v16, v17
	s_cbranch_vccz .LBB0_841
	v_max_f32_e32 v16, v16, v16
	v_max_f32_e32 v17, v172, v172
	v_max_f32_e32 v17, v17, v16
	v_sub_f32_e32 v16, v172, v17
	v_exp_f32_e32 v16, v16
	v_mov_b32_e32 v172, v17
	v_pk_mul_f32 v[80:81], v[80:81], v[16:17] op_sel_hi:[1,0]
	v_pk_mul_f32 v[78:79], v[78:79], v[16:17] op_sel_hi:[1,0]
	v_pk_mul_f32 v[76:77], v[76:77], v[16:17] op_sel_hi:[1,0]
	v_pk_mul_f32 v[74:75], v[74:75], v[16:17] op_sel_hi:[1,0]
	v_pk_mul_f32 v[72:73], v[72:73], v[16:17] op_sel_hi:[1,0]
	v_pk_mul_f32 v[70:71], v[70:71], v[16:17] op_sel_hi:[1,0]
	v_pk_mul_f32 v[68:69], v[68:69], v[16:17] op_sel_hi:[1,0]
	v_pk_mul_f32 v[66:67], v[66:67], v[16:17] op_sel_hi:[1,0]
	v_pk_mul_f32 v[64:65], v[64:65], v[16:17] op_sel_hi:[1,0]
	v_pk_mul_f32 v[62:63], v[62:63], v[16:17] op_sel_hi:[1,0]
	v_pk_mul_f32 v[60:61], v[60:61], v[16:17] op_sel_hi:[1,0]
	v_pk_mul_f32 v[58:59], v[58:59], v[16:17] op_sel_hi:[1,0]
	v_pk_mul_f32 v[56:57], v[56:57], v[16:17] op_sel_hi:[1,0]
	v_pk_mul_f32 v[54:55], v[54:55], v[16:17] op_sel_hi:[1,0]
	v_pk_mul_f32 v[52:53], v[52:53], v[16:17] op_sel_hi:[1,0]
	v_pk_mul_f32 v[50:51], v[50:51], v[16:17] op_sel_hi:[1,0]
	v_pk_mul_f32 v[48:49], v[48:49], v[16:17] op_sel_hi:[1,0]
	v_pk_mul_f32 v[46:47], v[46:47], v[16:17] op_sel_hi:[1,0]
	v_pk_mul_f32 v[44:45], v[44:45], v[16:17] op_sel_hi:[1,0]
	v_pk_mul_f32 v[42:43], v[42:43], v[16:17] op_sel_hi:[1,0]
	v_pk_mul_f32 v[40:41], v[40:41], v[16:17] op_sel_hi:[1,0]
	v_pk_mul_f32 v[38:39], v[38:39], v[16:17] op_sel_hi:[1,0]
	v_pk_mul_f32 v[36:37], v[36:37], v[16:17] op_sel_hi:[1,0]
	v_pk_mul_f32 v[34:35], v[34:35], v[16:17] op_sel_hi:[1,0]
	v_pk_mul_f32 v[32:33], v[32:33], v[16:17] op_sel_hi:[1,0]
	v_pk_mul_f32 v[30:31], v[30:31], v[16:17] op_sel_hi:[1,0]
	v_pk_mul_f32 v[28:29], v[28:29], v[16:17] op_sel_hi:[1,0]
	v_pk_mul_f32 v[26:27], v[26:27], v[16:17] op_sel_hi:[1,0]
	v_pk_mul_f32 v[24:25], v[24:25], v[16:17] op_sel_hi:[1,0]
	v_pk_mul_f32 v[22:23], v[22:23], v[16:17] op_sel_hi:[1,0]
	v_pk_mul_f32 v[20:21], v[20:21], v[16:17] op_sel_hi:[1,0]
	v_pk_mul_f32 v[18:19], v[18:19], v[16:17] op_sel_hi:[1,0]
	v_mul_f32_e32 v2, v2, v16

; __device__ __forceinline__ float sigm(float x) { return __builtin_amdgcn_rcpf(1.f + __builtin_amdgcn_exp2f(-1.4426950408889634f * x)); }
; __device__ __forceinline__ void st8(bf16_t* p, const f32x4& a, const f32x4& b) { u32x4 w; w.x = pk2(a[0], a[1]); w.y = pk2(a[2], a[3]); w.z = pk2(b[0], b[1]); w.w = pk2(b[2], b[3]); *(u32x4*)p = w; }
;     __device__ __forceinline__ void operator()(const f32x4 (&acc)[2][2][4][2], const Unit& u, int wr, int wc, int fr, int fq) const {
;         const int row0 = u.pm * 256 + wr * 64 + fr, col0 = u.pn * 128 + wc * 32 + 8 * fq;
; #pragma unroll
;         for (int ai = 0; ai < 2; ++ai)
; #pragma unroll
;             for (int m = 0; m < 4; ++m) {
;                 const int row = row0 + ai * 128 + m * 16; const float rs = 1.0f / sqrtf(ssq[row] * (1.f / D) + RMS_EPS);
;                 f32x4 v0, v1;
; #pragma unroll
;                 for (int e = 0; e < 4; ++e) { const float g0 = acc[ai][0][m][0][e] * rs, g1 = acc[ai][0][m][1][e] * rs;
;                     v0[e] = g0 * sigm(g0) * (acc[ai][1][m][0][e] * rs); v1[e] = g1 * sigm(g1) * (acc[ai][1][m][1][e] * rs); }
;                 st8(O + (size_t)row * DFF + col0, v0, v1);
;             }
;     }
.LBB0_1010:
	v_lshl_add_u32 v146, s4, 8, v1
	v_ashrrev_i32_e32 v147, 31, v146
	v_lshl_add_u64 v[148:149], v[146:147], 2, s[6:7]
	global_load_dword v147, v[148:149], off
	global_load_dword v173, v[148:149], off offset:64
	global_load_dword v174, v[148:149], off offset:128
	global_load_dword v175, v[148:149], off offset:192
	global_load_dword v176, v[148:149], off offset:512
	global_load_dword v177, v[148:149], off offset:576
	global_load_dword v178, v[148:149], off offset:640
	global_load_dword v179, v[148:149], off offset:704
	v_mov_b32_e32 v164, v124
	v_mov_b32_e32 v165, v116
	v_mov_b32_e32 v116, v125
	v_lshl_or_b32 v158, s5, 7, v151
	v_readlane_b32 s4, v255, 11
	v_readlane_b32 s5, v255, 12
	v_ashrrev_i32_e32 v159, 31, v158
	v_mov_b32_e32 v162, v122
	v_mov_b32_e32 v163, v114
	v_mov_b32_e32 v114, v123
	v_mov_b64_e32 v[122:123], s[4:5]
	v_mov_b32_e32 v160, v126
	v_mov_b32_e32 v161, v118
	v_mov_b32_e32 v118, v127
	v_mov_b32_e32 v126, v128
	v_mov_b32_e32 v127, v120
	v_mov_b32_e32 v120, v129
	v_mad_i64_i32 v[128:129], s[4:5], v146, s73, v[122:123]
	v_or_b32_e32 v166, 16, v146
	v_ashrrev_i32_e32 v167, 31, v166
	s_waitcnt vmcnt(0)
	v_fmamk_f32 v124, v147, 0x3a000000, v155
	v_mul_f32_e32 v125, 0x4f800000, v124
	v_cmp_gt_f32_e32 vcc, s72, v124
	s_nop 1
	v_cndmask_b32_e32 v147, v124, v125, vcc
	v_sqrt_f32_e32 v157, v147
	v_lshlrev_b64 v[124:125], 1, v[158:159]
	v_lshl_add_u64 v[128:129], v[128:129], 0, v[124:125]
	v_add_u32_e32 v158, -1, v157
	v_add_u32_e32 v159, 1, v157
	v_fma_f32 v168, -v158, v157, v147
	v_fma_f32 v169, -v159, v157, v147
	v_cmp_ge_f32_e64 s[4:5], 0, v168
	s_nop 1
	v_cndmask_b32_e64 v157, v157, v158, s[4:5]
	v_cmp_lt_f32_e64 s[4:5], 0, v169
	s_nop 1
	v_cndmask_b32_e64 v157, v157, v159, s[4:5]
	v_mul_f32_e32 v158, 0x37800000, v157
	v_cndmask_b32_e32 v157, v157, v158, vcc
	v_cmp_class_f32_e32 vcc, v147, v156
	v_lshl_add_u64 v[158:159], v[166:167], 2, s[6:7]
	s_nop 0
	v_cndmask_b32_e32 v147, v157, v147, vcc
	v_div_scale_f32 v157, s[4:5], v147, v147, 1.0
	v_rcp_f32_e32 v168, v157
	v_div_scale_f32 v167, vcc, 1.0, v147, 1.0
	v_fma_f32 v169, -v157, v168, 1.0
	v_fmac_f32_e32 v168, v169, v168
	v_mul_f32_e32 v169, v167, v168
	v_fma_f32 v170, -v157, v169, v167
	v_fmac_f32_e32 v169, v170, v168
	v_fma_f32 v157, -v157, v169, v167
	v_div_fmas_f32 v157, v157, v168, v169
	v_div_fixup_f32 v168, v157, v147, 1.0
	v_pk_mul_f32 v[118:119], v[118:119], v[168:169] op_sel_hi:[1,0]
	v_pk_mul_f32 v[114:115], v[114:115], v[168:169] op_sel_hi:[1,0]
	v_pk_mul_f32 v[126:127], v[126:127], v[168:169] op_sel_hi:[1,0]
	v_pk_mul_f32 v[116:117], v[116:117], v[168:169] op_sel_hi:[1,0]
	v_pk_mul_f32 v[160:161], v[160:161], v[168:169] op_sel_hi:[1,0]
	v_pk_mul_f32 v[162:163], v[162:163], v[168:169] op_sel_hi:[1,0]
	v_pk_mul_f32 v[164:165], v[164:165], v[168:169] op_sel_hi:[1,0]
	v_pk_mul_f32 v[120:121], v[120:121], v[168:169] op_sel_hi:[1,0]
	v_mul_f32_e32 v167, 0xbfb8aa3b, v119
	v_mul_f32_e32 v168, 0xbfb8aa3b, v115
	v_mul_f32_e32 v169, 0xbfb8aa3b, v127
	v_mul_f32_e32 v172, 0xbfb8aa3b, v117
	v_mul_f32_e32 v147, 0xbfb8aa3b, v161
	v_mul_f32_e32 v157, 0xbfb8aa3b, v163
	v_mul_f32_e32 v170, 0xbfb8aa3b, v165
	v_mul_f32_e32 v171, 0xbfb8aa3b, v121
	v_exp_f32_e32 v167, v167
	v_exp_f32_e32 v168, v168
	v_exp_f32_e32 v169, v169
	v_exp_f32_e32 v172, v172
	v_exp_f32_e32 v147, v147
	v_exp_f32_e32 v157, v157
	v_exp_f32_e32 v170, v170
	v_exp_f32_e32 v171, v171
	v_add_f32_e32 v167, 1.0, v167
	v_add_f32_e32 v168, 1.0, v168
	v_add_f32_e32 v169, 1.0, v169
	v_add_f32_e32 v172, 1.0, v172
	v_add_f32_e32 v147, 1.0, v147
	v_add_f32_e32 v157, 1.0, v157
	v_add_f32_e32 v170, 1.0, v170
	v_add_f32_e32 v171, 1.0, v171
	v_rcp_f32_e32 v167, v167
	v_rcp_f32_e32 v168, v168
	v_rcp_f32_e32 v169, v169
	v_rcp_f32_e32 v172, v172
	v_rcp_f32_e32 v147, v147
	v_rcp_f32_e32 v157, v157
	v_rcp_f32_e32 v170, v170
	v_rcp_f32_e32 v171, v171
	v_mul_f32_e32 v119, v119, v167
	v_mul_f32_e32 v115, v115, v168
	v_mul_f32_e32 v127, v127, v169
	v_mul_f32_e32 v117, v117, v172
	v_mul_f32_e32 v147, v161, v147
	v_mul_f32_e32 v157, v163, v157
	v_mul_f32_e32 v161, v165, v170
	v_mul_f32_e32 v121, v121, v171
	v_mul_f32_e32 v118, v118, v119
	v_mul_f32_e32 v119, v114, v115
	v_mul_f32_e32 v115, v126, v127
	v_mul_f32_e32 v117, v116, v117
	v_mul_f32_e32 v147, v160, v147
	v_mul_f32_e32 v157, v162, v157
	v_mul_f32_e32 v126, v164, v161
	v_mul_f32_e32 v120, v120, v121
	v_cvt_pk_bf16_f32 v114, v147, v118
	v_cvt_pk_bf16_f32 v115, v115, v120
	v_cvt_pk_bf16_f32 v116, v157, v119
	v_cvt_pk_bf16_f32 v117, v126, v117
	global_store_dwordx4 v[128:129], v[114:117], off
	s_nop 1
	v_mov_b32_e32 v118, v173
	s_nop 0
	v_mov_b32_e32 v115, v102
	v_mov_b32_e32 v102, v111
	v_mov_b32_e32 v111, v100
	v_mov_b32_e32 v100, v109
	v_mov_b32_e32 v116, v106
	v_mov_b32_e32 v106, v112
	v_mov_b32_e32 v117, v98
	v_mov_b32_e32 v98, v107
	v_mov_b32_e32 v107, v104
	v_mov_b32_e32 v104, v113
	v_mov_b32_e32 v114, v110
	v_mov_b32_e32 v110, v108
	v_or_b32_e32 v108, 32, v146
	v_fmamk_f32 v109, v118, 0x3a000000, v155
	v_mul_f32_e32 v112, 0x4f800000, v109
	v_cmp_gt_f32_e32 vcc, s72, v109
	s_nop 1
	v_cndmask_b32_e32 v118, v109, v112, vcc
	v_sqrt_f32_e32 v119, v118
	v_mad_i64_i32 v[112:113], s[4:5], v166, s73, v[122:123]
	v_ashrrev_i32_e32 v109, 31, v108
	v_add_u32_e32 v120, -1, v119
	v_add_u32_e32 v121, 1, v119
	v_fma_f32 v126, -v120, v119, v118
	v_fma_f32 v127, -v121, v119, v118
	v_cmp_ge_f32_e64 s[4:5], 0, v126
	v_lshl_add_u64 v[112:113], v[112:113], 0, v[124:125]
	s_nop 0
	v_cndmask_b32_e64 v119, v119, v120, s[4:5]
	v_cmp_lt_f32_e64 s[4:5], 0, v127
	s_nop 1
	v_cndmask_b32_e64 v119, v119, v121, s[4:5]
	v_mul_f32_e32 v120, 0x37800000, v119
	v_cndmask_b32_e32 v119, v119, v120, vcc
; __device__ __forceinline__ float sigm(float x) { return __builtin_amdgcn_rcpf(1.f + __builtin_amdgcn_exp2f(-1.4426950408889634f * x)); }
; __device__ __forceinline__ void st8(bf16_t* p, const f32x4& a, const f32x4& b) { u32x4 w; w.x = pk2(a[0], a[1]); w.y = pk2(a[2], a[3]); w.z = pk2(b[0], b[1]); w.w = pk2(b[2], b[3]); *(u32x4*)p = w; }
;     __device__ __forceinline__ void operator()(const f32x4 (&acc)[2][2][4][2], const Unit& u, int wr, int wc, int fr, int fq) const {
;         const int row0 = u.pm * 256 + wr * 64 + fr, col0 = u.pn * 128 + wc * 32 + 8 * fq;
; #pragma unroll
;         for (int ai = 0; ai < 2; ++ai)
; #pragma unroll
;             for (int m = 0; m < 4; ++m) {
;                 const int row = row0 + ai * 128 + m * 16; const float rs = 1.0f / sqrtf(ssq[row] * (1.f / D) + RMS_EPS);
;                 f32x4 v0, v1;
; #pragma unroll
;                 for (int e = 0; e < 4; ++e) { const float g0 = acc[ai][0][m][0][e] * rs, g1 = acc[ai][0][m][1][e] * rs;
;                     v0[e] = g0 * sigm(g0) * (acc[ai][1][m][0][e] * rs); v1[e] = g1 * sigm(g1) * (acc[ai][1][m][1][e] * rs); }
;                 st8(O + (size_t)row * DFF + col0, v0, v1);
;             }
;     }
	v_cmp_class_f32_e32 vcc, v118, v156
	s_nop 1
	v_cndmask_b32_e32 v120, v119, v118, vcc
	v_div_scale_f32 v121, s[4:5], v120, v120, 1.0
	v_rcp_f32_e32 v126, v121
	v_lshl_add_u64 v[118:119], v[108:109], 2, s[6:7]
	v_div_scale_f32 v109, vcc, 1.0, v120, 1.0
	v_fma_f32 v127, -v121, v126, 1.0
	v_fmac_f32_e32 v126, v127, v126
	v_mul_f32_e32 v127, v109, v126
	v_fma_f32 v128, -v121, v127, v109
	v_fmac_f32_e32 v127, v128, v126
	v_fma_f32 v109, -v121, v127, v109
	v_div_fmas_f32 v109, v109, v126, v127
	v_div_fixup_f32 v120, v109, v120, 1.0
	v_pk_mul_f32 v[102:103], v[102:103], v[120:121] op_sel_hi:[1,0]
	v_pk_mul_f32 v[98:99], v[98:99], v[120:121] op_sel_hi:[1,0]
	v_pk_mul_f32 v[106:107], v[106:107], v[120:121] op_sel_hi:[1,0]
	v_pk_mul_f32 v[100:101], v[100:101], v[120:121] op_sel_hi:[1,0]
	v_pk_mul_f32 v[114:115], v[114:115], v[120:121] op_sel_hi:[1,0]
	v_pk_mul_f32 v[116:117], v[116:117], v[120:121] op_sel_hi:[1,0]
	v_pk_mul_f32 v[110:111], v[110:111], v[120:121] op_sel_hi:[1,0]
	v_pk_mul_f32 v[104:105], v[104:105], v[120:121] op_sel_hi:[1,0]
	v_mul_f32_e32 v121, 0xbfb8aa3b, v103
	v_mul_f32_e32 v126, 0xbfb8aa3b, v99
	v_mul_f32_e32 v127, 0xbfb8aa3b, v107
	v_mul_f32_e32 v147, 0xbfb8aa3b, v101
	v_mul_f32_e32 v109, 0xbfb8aa3b, v115
	v_mul_f32_e32 v120, 0xbfb8aa3b, v117
	v_mul_f32_e32 v128, 0xbfb8aa3b, v111
	v_mul_f32_e32 v129, 0xbfb8aa3b, v105
	v_exp_f32_e32 v121, v121
	v_exp_f32_e32 v126, v126
	v_exp_f32_e32 v127, v127
	v_exp_f32_e32 v147, v147
	v_exp_f32_e32 v109, v109
	v_exp_f32_e32 v120, v120
	v_exp_f32_e32 v128, v128
	v_exp_f32_e32 v129, v129
	v_add_f32_e32 v121, 1.0, v121
	v_add_f32_e32 v126, 1.0, v126
	v_add_f32_e32 v127, 1.0, v127
	v_add_f32_e32 v147, 1.0, v147
	v_add_f32_e32 v109, 1.0, v109
	v_add_f32_e32 v120, 1.0, v120
	v_add_f32_e32 v128, 1.0, v128
	v_add_f32_e32 v129, 1.0, v129
	v_rcp_f32_e32 v121, v121
	v_rcp_f32_e32 v126, v126
	v_rcp_f32_e32 v127, v127
	v_rcp_f32_e32 v147, v147
	v_rcp_f32_e32 v109, v109
	v_rcp_f32_e32 v120, v120
	v_rcp_f32_e32 v128, v128
	v_rcp_f32_e32 v129, v129
	v_mul_f32_e32 v103, v103, v121
	v_mul_f32_e32 v99, v99, v126
	v_mul_f32_e32 v107, v107, v127
	v_mul_f32_e32 v101, v101, v147
	v_mul_f32_e32 v109, v115, v109
	v_mul_f32_e32 v115, v117, v120
	v_mul_f32_e32 v111, v111, v128
	v_mul_f32_e32 v105, v105, v129
	v_mul_f32_e32 v102, v102, v103
	v_mul_f32_e32 v103, v98, v99
	v_mul_f32_e32 v99, v106, v107
	v_mul_f32_e32 v101, v100, v101
	v_mul_f32_e32 v109, v114, v109
	v_mul_f32_e32 v114, v116, v115
	v_mul_f32_e32 v106, v110, v111
	v_mul_f32_e32 v104, v104, v105
	v_cvt_pk_bf16_f32 v98, v109, v102
	v_cvt_pk_bf16_f32 v99, v99, v104
	v_cvt_pk_bf16_f32 v100, v114, v103
	v_cvt_pk_bf16_f32 v101, v106, v101
	global_store_dwordx4 v[112:113], v[98:101], off
	s_nop 1
	v_mov_b32_e32 v102, v174
	s_nop 0
	v_mov_b32_e32 v99, v86
	v_mov_b32_e32 v86, v95
	v_mov_b32_e32 v95, v84
	v_mov_b32_e32 v84, v93
	v_mov_b32_e32 v100, v90
	v_mov_b32_e32 v90, v96
	v_mov_b32_e32 v101, v82
	v_mov_b32_e32 v82, v91
	v_mov_b32_e32 v91, v88
	v_mov_b32_e32 v88, v97
	v_mov_b32_e32 v98, v94
	v_mov_b32_e32 v94, v92
	v_or_b32_e32 v92, 48, v146
	v_fmamk_f32 v93, v102, 0x3a000000, v155
	v_mul_f32_e32 v96, 0x4f800000, v93
	v_cmp_gt_f32_e32 vcc, s72, v93
	s_nop 1
	v_cndmask_b32_e32 v102, v93, v96, vcc
	v_sqrt_f32_e32 v103, v102
	v_mad_i64_i32 v[96:97], s[4:5], v108, s73, v[122:123]
	v_ashrrev_i32_e32 v93, 31, v92
	v_add_u32_e32 v104, -1, v103
	v_add_u32_e32 v105, 1, v103
	v_fma_f32 v106, -v104, v103, v102
	v_fma_f32 v107, -v105, v103, v102
	v_cmp_ge_f32_e64 s[4:5], 0, v106
	v_lshl_add_u64 v[96:97], v[96:97], 0, v[124:125]
	s_nop 0
	v_cndmask_b32_e64 v103, v103, v104, s[4:5]
	v_cmp_lt_f32_e64 s[4:5], 0, v107
	s_nop 1
	v_cndmask_b32_e64 v103, v103, v105, s[4:5]
	v_mul_f32_e32 v104, 0x37800000, v103
	v_cndmask_b32_e32 v103, v103, v104, vcc
	v_cmp_class_f32_e32 vcc, v102, v156
	s_nop 1
	v_cndmask_b32_e32 v104, v103, v102, vcc
	v_div_scale_f32 v105, s[4:5], v104, v104, 1.0
	v_rcp_f32_e32 v106, v105
	v_lshl_add_u64 v[102:103], v[92:93], 2, s[6:7]
	v_div_scale_f32 v93, vcc, 1.0, v104, 1.0
	v_fma_f32 v107, -v105, v106, 1.0
	v_fmac_f32_e32 v106, v107, v106
	v_mul_f32_e32 v107, v93, v106
	v_fma_f32 v108, -v105, v107, v93
	v_fmac_f32_e32 v107, v108, v106
	v_fma_f32 v93, -v105, v107, v93
	v_div_fmas_f32 v93, v93, v106, v107
	v_div_fixup_f32 v104, v93, v104, 1.0
	v_pk_mul_f32 v[86:87], v[86:87], v[104:105] op_sel_hi:[1,0]
	v_pk_mul_f32 v[82:83], v[82:83], v[104:105] op_sel_hi:[1,0]
	v_pk_mul_f32 v[90:91], v[90:91], v[104:105] op_sel_hi:[1,0]
	v_pk_mul_f32 v[84:85], v[84:85], v[104:105] op_sel_hi:[1,0]
	v_pk_mul_f32 v[98:99], v[98:99], v[104:105] op_sel_hi:[1,0]
	v_pk_mul_f32 v[100:101], v[100:101], v[104:105] op_sel_hi:[1,0]
	v_pk_mul_f32 v[94:95], v[94:95], v[104:105] op_sel_hi:[1,0]
	v_pk_mul_f32 v[88:89], v[88:89], v[104:105] op_sel_hi:[1,0]
	v_mul_f32_e32 v105, 0xbfb8aa3b, v87
	v_mul_f32_e32 v106, 0xbfb8aa3b, v83
	v_mul_f32_e32 v107, 0xbfb8aa3b, v91
	v_mul_f32_e32 v110, 0xbfb8aa3b, v85
	v_mul_f32_e32 v93, 0xbfb8aa3b, v99
	v_mul_f32_e32 v104, 0xbfb8aa3b, v101
	v_mul_f32_e32 v108, 0xbfb8aa3b, v95
	v_mul_f32_e32 v109, 0xbfb8aa3b, v89
	v_exp_f32_e32 v105, v105
	v_exp_f32_e32 v106, v106
	v_exp_f32_e32 v107, v107
	v_exp_f32_e32 v110, v110
	v_exp_f32_e32 v93, v93
	v_exp_f32_e32 v104, v104
	v_exp_f32_e32 v108, v108
	v_exp_f32_e32 v109, v109
	v_add_f32_e32 v105, 1.0, v105
	v_add_f32_e32 v106, 1.0, v106
	v_add_f32_e32 v107, 1.0, v107
	v_add_f32_e32 v110, 1.0, v110
	v_add_f32_e32 v93, 1.0, v93
	v_add_f32_e32 v104, 1.0, v104
	v_add_f32_e32 v108, 1.0, v108
	v_add_f32_e32 v109, 1.0, v109
	v_rcp_f32_e32 v105, v105
	v_rcp_f32_e32 v106, v106
	v_rcp_f32_e32 v107, v107
	v_rcp_f32_e32 v110, v110
; __device__ __forceinline__ float sigm(float x) { return __builtin_amdgcn_rcpf(1.f + __builtin_amdgcn_exp2f(-1.4426950408889634f * x)); }
; __device__ __forceinline__ void st8(bf16_t* p, const f32x4& a, const f32x4& b) { u32x4 w; w.x = pk2(a[0], a[1]); w.y = pk2(a[2], a[3]); w.z = pk2(b[0], b[1]); w.w = pk2(b[2], b[3]); *(u32x4*)p = w; }
;     __device__ __forceinline__ void operator()(const f32x4 (&acc)[2][2][4][2], const Unit& u, int wr, int wc, int fr, int fq) const {
;         const int row0 = u.pm * 256 + wr * 64 + fr, col0 = u.pn * 128 + wc * 32 + 8 * fq;
; #pragma unroll
;         for (int ai = 0; ai < 2; ++ai)
; #pragma unroll
;             for (int m = 0; m < 4; ++m) {
;                 const int row = row0 + ai * 128 + m * 16; const float rs = 1.0f / sqrtf(ssq[row] * (1.f / D) + RMS_EPS);
;                 f32x4 v0, v1;
; #pragma unroll
;                 for (int e = 0; e < 4; ++e) { const float g0 = acc[ai][0][m][0][e] * rs, g1 = acc[ai][0][m][1][e] * rs;
;                     v0[e] = g0 * sigm(g0) * (acc[ai][1][m][0][e] * rs); v1[e] = g1 * sigm(g1) * (acc[ai][1][m][1][e] * rs); }
;                 st8(O + (size_t)row * DFF + col0, v0, v1);
;             }
;     }
	v_rcp_f32_e32 v93, v93
	v_rcp_f32_e32 v104, v104
	v_rcp_f32_e32 v108, v108
	v_rcp_f32_e32 v109, v109
	v_mul_f32_e32 v87, v87, v105
	v_mul_f32_e32 v83, v83, v106
	v_mul_f32_e32 v91, v91, v107
	v_mul_f32_e32 v85, v85, v110
	v_mul_f32_e32 v93, v99, v93
	v_mul_f32_e32 v99, v101, v104
	v_mul_f32_e32 v95, v95, v108
	v_mul_f32_e32 v89, v89, v109
	v_mul_f32_e32 v86, v86, v87
	v_mul_f32_e32 v87, v82, v83
	v_mul_f32_e32 v83, v90, v91
	v_mul_f32_e32 v85, v84, v85
	v_mul_f32_e32 v93, v98, v93
	v_mul_f32_e32 v98, v100, v99
	v_mul_f32_e32 v90, v94, v95
	v_mul_f32_e32 v88, v88, v89
	v_cvt_pk_bf16_f32 v82, v93, v86
	v_cvt_pk_bf16_f32 v83, v83, v88
	v_cvt_pk_bf16_f32 v84, v98, v87
	v_cvt_pk_bf16_f32 v85, v90, v85
	global_store_dwordx4 v[96:97], v[82:85], off
	s_nop 1
	v_mov_b32_e32 v86, v175
	s_nop 0
	v_mov_b32_e32 v83, v70
	v_mov_b32_e32 v70, v79
	v_mov_b32_e32 v79, v68
	v_mov_b32_e32 v82, v78
	v_mov_b32_e32 v78, v76
	v_mov_b32_e32 v84, v74
	v_mov_b32_e32 v74, v80
	v_mov_b32_e32 v85, v66
	v_mov_b32_e32 v66, v75
	v_mov_b32_e32 v75, v72
	v_mov_b32_e32 v72, v81
	v_fmamk_f32 v68, v86, 0x3a000000, v155
	v_mul_f32_e32 v76, 0x4f800000, v68
	v_cmp_gt_f32_e32 vcc, s72, v68
	s_nop 1
	v_cndmask_b32_e32 v80, v68, v76, vcc
	v_sqrt_f32_e32 v81, v80
	v_mov_b32_e32 v68, v77
	v_mad_i64_i32 v[76:77], s[4:5], v92, s73, v[122:123]
	v_add_u32_e32 v86, -1, v81
	v_add_u32_e32 v87, 1, v81
	v_fma_f32 v88, -v86, v81, v80
	v_fma_f32 v89, -v87, v81, v80
	v_cmp_ge_f32_e64 s[4:5], 0, v88
	v_lshl_add_u64 v[76:77], v[76:77], 0, v[124:125]
	s_nop 0
	v_cndmask_b32_e64 v81, v81, v86, s[4:5]
	v_cmp_lt_f32_e64 s[4:5], 0, v89
	s_nop 1
	v_cndmask_b32_e64 v81, v81, v87, s[4:5]
	v_mul_f32_e32 v86, 0x37800000, v81
	v_cndmask_b32_e32 v81, v81, v86, vcc
	v_cmp_class_f32_e32 vcc, v80, v156
	s_nop 1
	v_cndmask_b32_e32 v80, v81, v80, vcc
	v_div_scale_f32 v81, s[4:5], v80, v80, 1.0
	v_rcp_f32_e32 v86, v81
	v_div_scale_f32 v87, vcc, 1.0, v80, 1.0
	v_fma_f32 v88, -v81, v86, 1.0
	v_fmac_f32_e32 v86, v88, v86
	v_mul_f32_e32 v88, v87, v86
	v_fma_f32 v89, -v81, v88, v87
	v_fmac_f32_e32 v88, v89, v86
	v_fma_f32 v81, -v81, v88, v87
	v_div_fmas_f32 v81, v81, v86, v88
	v_div_fixup_f32 v80, v81, v80, 1.0
	v_pk_mul_f32 v[70:71], v[70:71], v[80:81] op_sel_hi:[1,0]
	v_pk_mul_f32 v[66:67], v[66:67], v[80:81] op_sel_hi:[1,0]
	v_pk_mul_f32 v[74:75], v[74:75], v[80:81] op_sel_hi:[1,0]
	v_pk_mul_f32 v[68:69], v[68:69], v[80:81] op_sel_hi:[1,0]
	v_pk_mul_f32 v[82:83], v[82:83], v[80:81] op_sel_hi:[1,0]
	v_pk_mul_f32 v[84:85], v[84:85], v[80:81] op_sel_hi:[1,0]
	v_pk_mul_f32 v[78:79], v[78:79], v[80:81] op_sel_hi:[1,0]
	v_pk_mul_f32 v[72:73], v[72:73], v[80:81] op_sel_hi:[1,0]
	v_mul_f32_e32 v86, 0xbfb8aa3b, v71
	v_mul_f32_e32 v87, 0xbfb8aa3b, v67
	v_mul_f32_e32 v88, 0xbfb8aa3b, v75
	v_mul_f32_e32 v91, 0xbfb8aa3b, v69
	v_mul_f32_e32 v80, 0xbfb8aa3b, v83
	v_mul_f32_e32 v81, 0xbfb8aa3b, v85
	v_mul_f32_e32 v89, 0xbfb8aa3b, v79
	v_mul_f32_e32 v90, 0xbfb8aa3b, v73
	v_exp_f32_e32 v86, v86
	v_exp_f32_e32 v87, v87
	v_exp_f32_e32 v88, v88
	v_exp_f32_e32 v91, v91
	v_exp_f32_e32 v80, v80
	v_exp_f32_e32 v81, v81
	v_exp_f32_e32 v89, v89
	v_exp_f32_e32 v90, v90
	v_add_f32_e32 v86, 1.0, v86
	v_add_f32_e32 v87, 1.0, v87
	v_add_f32_e32 v88, 1.0, v88
	v_add_f32_e32 v91, 1.0, v91
	v_add_f32_e32 v80, 1.0, v80
	v_add_f32_e32 v81, 1.0, v81
	v_add_f32_e32 v89, 1.0, v89
	v_add_f32_e32 v90, 1.0, v90
	v_rcp_f32_e32 v86, v86
	v_rcp_f32_e32 v87, v87
	v_rcp_f32_e32 v88, v88
	v_rcp_f32_e32 v91, v91
	v_rcp_f32_e32 v80, v80
	v_rcp_f32_e32 v81, v81
	v_rcp_f32_e32 v89, v89
	v_rcp_f32_e32 v90, v90
	v_mul_f32_e32 v71, v71, v86
	v_mul_f32_e32 v67, v67, v87
	v_mul_f32_e32 v75, v75, v88
	v_mul_f32_e32 v69, v69, v91
	v_mul_f32_e32 v80, v83, v80
	v_mul_f32_e32 v81, v85, v81
	v_mul_f32_e32 v79, v79, v89
	v_mul_f32_e32 v73, v73, v90
	v_mul_f32_e32 v70, v70, v71
	v_mul_f32_e32 v71, v66, v67
	v_mul_f32_e32 v67, v74, v75
	v_mul_f32_e32 v69, v68, v69
	v_mul_f32_e32 v80, v82, v80
	v_mul_f32_e32 v81, v84, v81
	v_mul_f32_e32 v74, v78, v79
	v_mul_f32_e32 v72, v72, v73
	v_cvt_pk_bf16_f32 v66, v80, v70
	v_cvt_pk_bf16_f32 v67, v67, v72
	v_cvt_pk_bf16_f32 v68, v81, v71
	v_cvt_pk_bf16_f32 v69, v74, v69
	global_store_dwordx4 v[76:77], v[66:69], off
	s_nop 1
	v_mov_b32_e32 v70, v176
	s_nop 0
	v_mov_b32_e32 v66, v62
	v_mov_b32_e32 v62, v60
	v_mov_b32_e32 v67, v54
	v_mov_b32_e32 v54, v63
	v_mov_b32_e32 v63, v52
	v_mov_b32_e32 v52, v61
	v_mov_b32_e32 v68, v58
	v_mov_b32_e32 v58, v64
	v_mov_b32_e32 v69, v50
	v_mov_b32_e32 v50, v59
	v_mov_b32_e32 v59, v56
	v_mov_b32_e32 v56, v65
	v_fmamk_f32 v60, v70, 0x3a000000, v155
	v_mul_f32_e32 v61, 0x4f800000, v60
	v_cmp_gt_f32_e32 vcc, s72, v60
	s_nop 1
	v_cndmask_b32_e32 v64, v60, v61, vcc
	v_sqrt_f32_e32 v65, v64
	v_add_u32_e32 v60, 0x80, v146
	v_mad_i64_i32 v[60:61], s[4:5], v60, s73, v[122:123]
	v_add_u32_e32 v70, -1, v65
	v_add_u32_e32 v71, 1, v65
	v_fma_f32 v72, -v70, v65, v64
	v_fma_f32 v73, -v71, v65, v64
	v_cmp_ge_f32_e64 s[4:5], 0, v72
	v_lshl_add_u64 v[60:61], v[60:61], 0, v[124:125]
	s_nop 0
	v_cndmask_b32_e64 v65, v65, v70, s[4:5]
	v_cmp_lt_f32_e64 s[4:5], 0, v73
	s_nop 1
	v_cndmask_b32_e64 v65, v65, v71, s[4:5]
	v_mul_f32_e32 v70, 0x37800000, v65
	v_cndmask_b32_e32 v65, v65, v70, vcc
	v_cmp_class_f32_e32 vcc, v64, v156
	s_nop 1
	v_cndmask_b32_e32 v64, v65, v64, vcc
	v_div_scale_f32 v65, s[4:5], v64, v64, 1.0
	v_rcp_f32_e32 v70, v65
	v_div_scale_f32 v71, vcc, 1.0, v64, 1.0
	v_fma_f32 v72, -v65, v70, 1.0
	v_fmac_f32_e32 v70, v72, v70
	v_mul_f32_e32 v72, v71, v70
	v_fma_f32 v73, -v65, v72, v71
	v_fmac_f32_e32 v72, v73, v70
	v_fma_f32 v65, -v65, v72, v71
	v_div_fmas_f32 v65, v65, v70, v72
	v_div_fixup_f32 v64, v65, v64, 1.0
; __device__ __forceinline__ float sigm(float x) { return __builtin_amdgcn_rcpf(1.f + __builtin_amdgcn_exp2f(-1.4426950408889634f * x)); }
; __device__ __forceinline__ void st8(bf16_t* p, const f32x4& a, const f32x4& b) { u32x4 w; w.x = pk2(a[0], a[1]); w.y = pk2(a[2], a[3]); w.z = pk2(b[0], b[1]); w.w = pk2(b[2], b[3]); *(u32x4*)p = w; }
;     __device__ __forceinline__ void operator()(const f32x4 (&acc)[2][2][4][2], const Unit& u, int wr, int wc, int fr, int fq) const {
;         const int row0 = u.pm * 256 + wr * 64 + fr, col0 = u.pn * 128 + wc * 32 + 8 * fq;
; #pragma unroll
;         for (int ai = 0; ai < 2; ++ai)
; #pragma unroll
;             for (int m = 0; m < 4; ++m) {
;                 const int row = row0 + ai * 128 + m * 16; const float rs = 1.0f / sqrtf(ssq[row] * (1.f / D) + RMS_EPS);
;                 f32x4 v0, v1;
; #pragma unroll
;                 for (int e = 0; e < 4; ++e) { const float g0 = acc[ai][0][m][0][e] * rs, g1 = acc[ai][0][m][1][e] * rs;
;                     v0[e] = g0 * sigm(g0) * (acc[ai][1][m][0][e] * rs); v1[e] = g1 * sigm(g1) * (acc[ai][1][m][1][e] * rs); }
;                 st8(O + (size_t)row * DFF + col0, v0, v1);
;             }
;     }
	v_pk_mul_f32 v[54:55], v[54:55], v[64:65] op_sel_hi:[1,0]
	v_pk_mul_f32 v[50:51], v[50:51], v[64:65] op_sel_hi:[1,0]
	v_pk_mul_f32 v[58:59], v[58:59], v[64:65] op_sel_hi:[1,0]
	v_pk_mul_f32 v[52:53], v[52:53], v[64:65] op_sel_hi:[1,0]
	v_pk_mul_f32 v[66:67], v[66:67], v[64:65] op_sel_hi:[1,0]
	v_pk_mul_f32 v[68:69], v[68:69], v[64:65] op_sel_hi:[1,0]
	v_pk_mul_f32 v[62:63], v[62:63], v[64:65] op_sel_hi:[1,0]
	v_pk_mul_f32 v[56:57], v[56:57], v[64:65] op_sel_hi:[1,0]
	v_mul_f32_e32 v70, 0xbfb8aa3b, v55
	v_mul_f32_e32 v71, 0xbfb8aa3b, v51
	v_mul_f32_e32 v72, 0xbfb8aa3b, v59
	v_mul_f32_e32 v75, 0xbfb8aa3b, v53
	v_mul_f32_e32 v64, 0xbfb8aa3b, v67
	v_mul_f32_e32 v65, 0xbfb8aa3b, v69
	v_mul_f32_e32 v73, 0xbfb8aa3b, v63
	v_mul_f32_e32 v74, 0xbfb8aa3b, v57
	v_exp_f32_e32 v70, v70
	v_exp_f32_e32 v71, v71
	v_exp_f32_e32 v72, v72
	v_exp_f32_e32 v75, v75
	v_exp_f32_e32 v64, v64
	v_exp_f32_e32 v65, v65
	v_exp_f32_e32 v73, v73
	v_exp_f32_e32 v74, v74
	v_add_f32_e32 v70, 1.0, v70
	v_add_f32_e32 v71, 1.0, v71
	v_add_f32_e32 v72, 1.0, v72
	v_add_f32_e32 v75, 1.0, v75
	v_add_f32_e32 v64, 1.0, v64
	v_add_f32_e32 v65, 1.0, v65
	v_add_f32_e32 v73, 1.0, v73
	v_add_f32_e32 v74, 1.0, v74
	v_rcp_f32_e32 v70, v70
	v_rcp_f32_e32 v71, v71
	v_rcp_f32_e32 v72, v72
	v_rcp_f32_e32 v75, v75
	v_rcp_f32_e32 v64, v64
	v_rcp_f32_e32 v65, v65
	v_rcp_f32_e32 v73, v73
	v_rcp_f32_e32 v74, v74
	v_mul_f32_e32 v55, v55, v70
	v_mul_f32_e32 v51, v51, v71
	v_mul_f32_e32 v59, v59, v72
	v_mul_f32_e32 v53, v53, v75
	v_mul_f32_e32 v64, v67, v64
	v_mul_f32_e32 v65, v69, v65
	v_mul_f32_e32 v63, v63, v73
	v_mul_f32_e32 v57, v57, v74
	v_mul_f32_e32 v54, v54, v55
	v_mul_f32_e32 v55, v50, v51
	v_mul_f32_e32 v51, v58, v59
	v_mul_f32_e32 v53, v52, v53
	v_mul_f32_e32 v64, v66, v64
	v_mul_f32_e32 v65, v68, v65
	v_mul_f32_e32 v58, v62, v63
	v_mul_f32_e32 v56, v56, v57
	v_cvt_pk_bf16_f32 v50, v64, v54
	v_cvt_pk_bf16_f32 v51, v51, v56
	v_cvt_pk_bf16_f32 v52, v65, v55
	v_cvt_pk_bf16_f32 v53, v58, v53
	global_store_dwordx4 v[60:61], v[50:53], off
	s_nop 1
	v_mov_b32_e32 v54, v177
	s_nop 0
	v_mov_b32_e32 v50, v46
	v_mov_b32_e32 v46, v44
	v_mov_b32_e32 v51, v38
	v_mov_b32_e32 v38, v47
	v_mov_b32_e32 v47, v36
	v_mov_b32_e32 v36, v45
	v_mov_b32_e32 v52, v42
	v_mov_b32_e32 v42, v48
	v_mov_b32_e32 v53, v34
	v_mov_b32_e32 v34, v43
	v_mov_b32_e32 v43, v40
	v_mov_b32_e32 v40, v49
	v_fmamk_f32 v44, v54, 0x3a000000, v155
	v_mul_f32_e32 v45, 0x4f800000, v44
	v_cmp_gt_f32_e32 vcc, s72, v44
	s_nop 1
	v_cndmask_b32_e32 v48, v44, v45, vcc
	v_sqrt_f32_e32 v49, v48
	v_add_u32_e32 v44, 0x90, v146
	v_mad_i64_i32 v[44:45], s[4:5], v44, s73, v[122:123]
	v_add_u32_e32 v54, -1, v49
	v_add_u32_e32 v55, 1, v49
	v_fma_f32 v56, -v54, v49, v48
	v_fma_f32 v57, -v55, v49, v48
	v_cmp_ge_f32_e64 s[4:5], 0, v56
	v_lshl_add_u64 v[44:45], v[44:45], 0, v[124:125]
	s_nop 0
	v_cndmask_b32_e64 v49, v49, v54, s[4:5]
	v_cmp_lt_f32_e64 s[4:5], 0, v57
	s_nop 1
	v_cndmask_b32_e64 v49, v49, v55, s[4:5]
	v_mul_f32_e32 v54, 0x37800000, v49
	v_cndmask_b32_e32 v49, v49, v54, vcc
	v_cmp_class_f32_e32 vcc, v48, v156
	s_nop 1
	v_cndmask_b32_e32 v48, v49, v48, vcc
	v_div_scale_f32 v49, s[4:5], v48, v48, 1.0
	v_rcp_f32_e32 v54, v49
	v_div_scale_f32 v55, vcc, 1.0, v48, 1.0
	v_fma_f32 v56, -v49, v54, 1.0
	v_fmac_f32_e32 v54, v56, v54
	v_mul_f32_e32 v56, v55, v54
	v_fma_f32 v57, -v49, v56, v55
	v_fmac_f32_e32 v56, v57, v54
	v_fma_f32 v49, -v49, v56, v55
	v_div_fmas_f32 v49, v49, v54, v56
	v_div_fixup_f32 v48, v49, v48, 1.0
	v_pk_mul_f32 v[38:39], v[38:39], v[48:49] op_sel_hi:[1,0]
	v_pk_mul_f32 v[34:35], v[34:35], v[48:49] op_sel_hi:[1,0]
	v_pk_mul_f32 v[42:43], v[42:43], v[48:49] op_sel_hi:[1,0]
	v_pk_mul_f32 v[36:37], v[36:37], v[48:49] op_sel_hi:[1,0]
	v_pk_mul_f32 v[50:51], v[50:51], v[48:49] op_sel_hi:[1,0]
	v_pk_mul_f32 v[52:53], v[52:53], v[48:49] op_sel_hi:[1,0]
	v_pk_mul_f32 v[46:47], v[46:47], v[48:49] op_sel_hi:[1,0]
	v_pk_mul_f32 v[40:41], v[40:41], v[48:49] op_sel_hi:[1,0]
	v_mul_f32_e32 v54, 0xbfb8aa3b, v39
	v_mul_f32_e32 v55, 0xbfb8aa3b, v35
	v_mul_f32_e32 v56, 0xbfb8aa3b, v43
	v_mul_f32_e32 v59, 0xbfb8aa3b, v37
	v_mul_f32_e32 v48, 0xbfb8aa3b, v51
	v_mul_f32_e32 v49, 0xbfb8aa3b, v53
	v_mul_f32_e32 v57, 0xbfb8aa3b, v47
	v_mul_f32_e32 v58, 0xbfb8aa3b, v41
	v_exp_f32_e32 v54, v54
	v_exp_f32_e32 v55, v55
	v_exp_f32_e32 v56, v56
	v_exp_f32_e32 v59, v59
	v_exp_f32_e32 v48, v48
	v_exp_f32_e32 v49, v49
	v_exp_f32_e32 v57, v57
	v_exp_f32_e32 v58, v58
	v_add_f32_e32 v54, 1.0, v54
	v_add_f32_e32 v55, 1.0, v55
	v_add_f32_e32 v56, 1.0, v56
	v_add_f32_e32 v59, 1.0, v59
	v_add_f32_e32 v48, 1.0, v48
	v_add_f32_e32 v49, 1.0, v49
	v_add_f32_e32 v57, 1.0, v57
	v_add_f32_e32 v58, 1.0, v58
	v_rcp_f32_e32 v54, v54
	v_rcp_f32_e32 v55, v55
	v_rcp_f32_e32 v56, v56
	v_rcp_f32_e32 v59, v59
	v_rcp_f32_e32 v48, v48
	v_rcp_f32_e32 v49, v49
	v_rcp_f32_e32 v57, v57
	v_rcp_f32_e32 v58, v58
	v_mul_f32_e32 v39, v39, v54
	v_mul_f32_e32 v35, v35, v55
	v_mul_f32_e32 v43, v43, v56
	v_mul_f32_e32 v37, v37, v59
	v_mul_f32_e32 v48, v51, v48
	v_mul_f32_e32 v49, v53, v49
	v_mul_f32_e32 v47, v47, v57
	v_mul_f32_e32 v41, v41, v58
	v_mul_f32_e32 v38, v38, v39
	v_mul_f32_e32 v39, v34, v35
	v_mul_f32_e32 v35, v42, v43
	v_mul_f32_e32 v37, v36, v37
	v_mul_f32_e32 v48, v50, v48
	v_mul_f32_e32 v49, v52, v49
	v_mul_f32_e32 v42, v46, v47
	v_mul_f32_e32 v40, v40, v41
	v_cvt_pk_bf16_f32 v34, v48, v38
	v_cvt_pk_bf16_f32 v35, v35, v40
	v_cvt_pk_bf16_f32 v36, v49, v39
	v_cvt_pk_bf16_f32 v37, v42, v37
	global_store_dwordx4 v[44:45], v[34:37], off
	s_nop 1
	v_mov_b32_e32 v38, v178
	s_nop 0
	v_mov_b32_e32 v34, v30
	v_mov_b32_e32 v30, v28
	v_mov_b32_e32 v35, v22
	v_mov_b32_e32 v22, v31
	v_mov_b32_e32 v31, v20
; __device__ __forceinline__ float sigm(float x) { return __builtin_amdgcn_rcpf(1.f + __builtin_amdgcn_exp2f(-1.4426950408889634f * x)); }
; __device__ __forceinline__ void st8(bf16_t* p, const f32x4& a, const f32x4& b) { u32x4 w; w.x = pk2(a[0], a[1]); w.y = pk2(a[2], a[3]); w.z = pk2(b[0], b[1]); w.w = pk2(b[2], b[3]); *(u32x4*)p = w; }
;     __device__ __forceinline__ void operator()(const f32x4 (&acc)[2][2][4][2], const Unit& u, int wr, int wc, int fr, int fq) const {
;         const int row0 = u.pm * 256 + wr * 64 + fr, col0 = u.pn * 128 + wc * 32 + 8 * fq;
; #pragma unroll
;         for (int ai = 0; ai < 2; ++ai)
; #pragma unroll
;             for (int m = 0; m < 4; ++m) {
;                 const int row = row0 + ai * 128 + m * 16; const float rs = 1.0f / sqrtf(ssq[row] * (1.f / D) + RMS_EPS);
;                 f32x4 v0, v1;
; #pragma unroll
;                 for (int e = 0; e < 4; ++e) { const float g0 = acc[ai][0][m][0][e] * rs, g1 = acc[ai][0][m][1][e] * rs;
;                     v0[e] = g0 * sigm(g0) * (acc[ai][1][m][0][e] * rs); v1[e] = g1 * sigm(g1) * (acc[ai][1][m][1][e] * rs); }
;                 st8(O + (size_t)row * DFF + col0, v0, v1);
;             }
;     }
	v_mov_b32_e32 v20, v29
	v_mov_b32_e32 v36, v26
	v_mov_b32_e32 v26, v32
	v_mov_b32_e32 v37, v18
	v_mov_b32_e32 v18, v27
	v_mov_b32_e32 v27, v24
	v_mov_b32_e32 v24, v33
	v_fmamk_f32 v28, v38, 0x3a000000, v155
	v_mul_f32_e32 v29, 0x4f800000, v28
	v_cmp_gt_f32_e32 vcc, s72, v28
	s_nop 1
	v_cndmask_b32_e32 v32, v28, v29, vcc
	v_sqrt_f32_e32 v33, v32
	v_add_u32_e32 v28, 0xa0, v146
	v_mad_i64_i32 v[28:29], s[4:5], v28, s73, v[122:123]
	v_add_u32_e32 v38, -1, v33
	v_add_u32_e32 v39, 1, v33
	v_fma_f32 v40, -v38, v33, v32
	v_fma_f32 v41, -v39, v33, v32
	v_cmp_ge_f32_e64 s[4:5], 0, v40
	v_lshl_add_u64 v[28:29], v[28:29], 0, v[124:125]
	s_nop 0
	v_cndmask_b32_e64 v33, v33, v38, s[4:5]
	v_cmp_lt_f32_e64 s[4:5], 0, v41
	s_nop 1
	v_cndmask_b32_e64 v33, v33, v39, s[4:5]
	v_mul_f32_e32 v38, 0x37800000, v33
	v_cndmask_b32_e32 v33, v33, v38, vcc
	v_cmp_class_f32_e32 vcc, v32, v156
	s_nop 1
	v_cndmask_b32_e32 v32, v33, v32, vcc
	v_div_scale_f32 v33, s[4:5], v32, v32, 1.0
	v_rcp_f32_e32 v38, v33
	v_div_scale_f32 v39, vcc, 1.0, v32, 1.0
	v_fma_f32 v40, -v33, v38, 1.0
	v_fmac_f32_e32 v38, v40, v38
	v_mul_f32_e32 v40, v39, v38
	v_fma_f32 v41, -v33, v40, v39
	v_fmac_f32_e32 v40, v41, v38
	v_fma_f32 v33, -v33, v40, v39
	v_div_fmas_f32 v33, v33, v38, v40
	v_div_fixup_f32 v32, v33, v32, 1.0
	v_pk_mul_f32 v[22:23], v[22:23], v[32:33] op_sel_hi:[1,0]
	v_pk_mul_f32 v[18:19], v[18:19], v[32:33] op_sel_hi:[1,0]
	v_pk_mul_f32 v[26:27], v[26:27], v[32:33] op_sel_hi:[1,0]
	v_pk_mul_f32 v[20:21], v[20:21], v[32:33] op_sel_hi:[1,0]
	v_pk_mul_f32 v[34:35], v[34:35], v[32:33] op_sel_hi:[1,0]
	v_pk_mul_f32 v[36:37], v[36:37], v[32:33] op_sel_hi:[1,0]
	v_pk_mul_f32 v[30:31], v[30:31], v[32:33] op_sel_hi:[1,0]
	v_pk_mul_f32 v[24:25], v[24:25], v[32:33] op_sel_hi:[1,0]
	v_mul_f32_e32 v38, 0xbfb8aa3b, v23
	v_mul_f32_e32 v39, 0xbfb8aa3b, v19
	v_mul_f32_e32 v40, 0xbfb8aa3b, v27
	v_mul_f32_e32 v43, 0xbfb8aa3b, v21
	v_mul_f32_e32 v32, 0xbfb8aa3b, v35
	v_mul_f32_e32 v33, 0xbfb8aa3b, v37
	v_mul_f32_e32 v41, 0xbfb8aa3b, v31
	v_mul_f32_e32 v42, 0xbfb8aa3b, v25
	v_exp_f32_e32 v38, v38
	v_exp_f32_e32 v39, v39
	v_exp_f32_e32 v40, v40
	v_exp_f32_e32 v43, v43
	v_exp_f32_e32 v32, v32
	v_exp_f32_e32 v33, v33
	v_exp_f32_e32 v41, v41
	v_exp_f32_e32 v42, v42
	v_add_f32_e32 v38, 1.0, v38
	v_add_f32_e32 v39, 1.0, v39
	v_add_f32_e32 v40, 1.0, v40
	v_add_f32_e32 v43, 1.0, v43
	v_add_f32_e32 v32, 1.0, v32
	v_add_f32_e32 v33, 1.0, v33
	v_add_f32_e32 v41, 1.0, v41
	v_add_f32_e32 v42, 1.0, v42
	v_rcp_f32_e32 v38, v38
	v_rcp_f32_e32 v39, v39
	v_rcp_f32_e32 v40, v40
	v_rcp_f32_e32 v43, v43
	v_rcp_f32_e32 v32, v32
	v_rcp_f32_e32 v33, v33
	v_rcp_f32_e32 v41, v41
	v_rcp_f32_e32 v42, v42
	v_mul_f32_e32 v23, v23, v38
	v_mul_f32_e32 v19, v19, v39
	v_mul_f32_e32 v27, v27, v40
	v_mul_f32_e32 v21, v21, v43
	v_mul_f32_e32 v32, v35, v32
	v_mul_f32_e32 v33, v37, v33
	v_mul_f32_e32 v31, v31, v41
	v_mul_f32_e32 v25, v25, v42
	v_mul_f32_e32 v22, v22, v23
	v_mul_f32_e32 v23, v18, v19
	v_mul_f32_e32 v19, v26, v27
	v_mul_f32_e32 v21, v20, v21
	v_mul_f32_e32 v32, v34, v32
	v_mul_f32_e32 v33, v36, v33
	v_mul_f32_e32 v26, v30, v31
	v_mul_f32_e32 v24, v24, v25
	v_cvt_pk_bf16_f32 v18, v32, v22
	v_cvt_pk_bf16_f32 v19, v19, v24
	v_cvt_pk_bf16_f32 v20, v33, v23
	v_cvt_pk_bf16_f32 v21, v26, v21
	global_store_dwordx4 v[28:29], v[18:21], off
	s_nop 1
	v_mov_b32_e32 v22, v179
	s_nop 0
	v_mov_b32_e32 v19, v6
	v_mov_b32_e32 v6, v15
	v_mov_b32_e32 v15, v4
	v_mov_b32_e32 v4, v13
	v_mov_b32_e32 v20, v10
	v_mov_b32_e32 v10, v16
	v_mov_b32_e32 v21, v2
	v_mov_b32_e32 v2, v11
	v_mov_b32_e32 v11, v8
	v_mov_b32_e32 v8, v17
	v_mov_b32_e32 v18, v14
	v_mov_b32_e32 v14, v12
	v_add_u32_e32 v12, 0xb0, v146
	v_fmamk_f32 v13, v22, 0x3a000000, v155
	v_mul_f32_e32 v16, 0x4f800000, v13
	v_cmp_gt_f32_e32 vcc, s72, v13
	s_nop 1
	v_cndmask_b32_e32 v16, v13, v16, vcc
	v_sqrt_f32_e32 v17, v16
	v_mad_i64_i32 v[12:13], s[4:5], v12, s73, v[122:123]
	v_lshl_add_u64 v[12:13], v[12:13], 0, v[124:125]
	v_add_u32_e32 v22, -1, v17
	v_add_u32_e32 v23, 1, v17
	v_fma_f32 v24, -v22, v17, v16
	v_fma_f32 v25, -v23, v17, v16
	v_cmp_ge_f32_e64 s[4:5], 0, v24
	s_nop 1
	v_cndmask_b32_e64 v17, v17, v22, s[4:5]
	v_cmp_lt_f32_e64 s[4:5], 0, v25
	s_nop 1
	v_cndmask_b32_e64 v17, v17, v23, s[4:5]
	v_mul_f32_e32 v22, 0x37800000, v17
	v_cndmask_b32_e32 v17, v17, v22, vcc
	v_cmp_class_f32_e32 vcc, v16, v156
	s_nop 1
	v_cndmask_b32_e32 v16, v17, v16, vcc
	v_div_scale_f32 v17, s[4:5], v16, v16, 1.0
	v_rcp_f32_e32 v22, v17
	v_div_scale_f32 v23, vcc, 1.0, v16, 1.0
	v_fma_f32 v24, -v17, v22, 1.0
	v_fmac_f32_e32 v22, v24, v22
	v_mul_f32_e32 v24, v23, v22
	v_fma_f32 v25, -v17, v24, v23
	v_fmac_f32_e32 v24, v25, v22
	v_fma_f32 v17, -v17, v24, v23
	v_div_fmas_f32 v17, v17, v22, v24
	v_div_fixup_f32 v16, v17, v16, 1.0
	v_pk_mul_f32 v[6:7], v[6:7], v[16:17] op_sel_hi:[1,0]
	v_pk_mul_f32 v[2:3], v[2:3], v[16:17] op_sel_hi:[1,0]
	v_pk_mul_f32 v[10:11], v[10:11], v[16:17] op_sel_hi:[1,0]
	v_pk_mul_f32 v[4:5], v[4:5], v[16:17] op_sel_hi:[1,0]
	v_pk_mul_f32 v[18:19], v[18:19], v[16:17] op_sel_hi:[1,0]
	v_pk_mul_f32 v[20:21], v[20:21], v[16:17] op_sel_hi:[1,0]
	v_pk_mul_f32 v[14:15], v[14:15], v[16:17] op_sel_hi:[1,0]
	v_pk_mul_f32 v[8:9], v[8:9], v[16:17] op_sel_hi:[1,0]
	v_mul_f32_e32 v22, 0xbfb8aa3b, v7
	v_mul_f32_e32 v23, 0xbfb8aa3b, v3
	v_mul_f32_e32 v24, 0xbfb8aa3b, v11
	v_mul_f32_e32 v27, 0xbfb8aa3b, v5
	v_mul_f32_e32 v16, 0xbfb8aa3b, v19
	v_mul_f32_e32 v17, 0xbfb8aa3b, v21
	v_mul_f32_e32 v25, 0xbfb8aa3b, v15
	v_mul_f32_e32 v26, 0xbfb8aa3b, v9
	v_exp_f32_e32 v22, v22
	v_exp_f32_e32 v23, v23
	v_exp_f32_e32 v24, v24
	v_exp_f32_e32 v27, v27
	v_exp_f32_e32 v16, v16
	v_exp_f32_e32 v17, v17
	v_exp_f32_e32 v25, v25
	v_exp_f32_e32 v26, v26
	v_add_f32_e32 v22, 1.0, v22
	v_add_f32_e32 v23, 1.0, v23
	v_add_f32_e32 v24, 1.0, v24
	v_add_f32_e32 v27, 1.0, v27
	v_add_f32_e32 v16, 1.0, v16
	v_add_f32_e32 v17, 1.0, v17
	v_add_f32_e32 v25, 1.0, v25
	v_add_f32_e32 v26, 1.0, v26
	v_rcp_f32_e32 v22, v22
	v_rcp_f32_e32 v23, v23
	v_rcp_f32_e32 v24, v24
	v_rcp_f32_e32 v27, v27
	v_rcp_f32_e32 v16, v16
	v_rcp_f32_e32 v17, v17
	v_rcp_f32_e32 v25, v25
	v_rcp_f32_e32 v26, v26
	v_mul_f32_e32 v7, v7, v22
	v_mul_f32_e32 v3, v3, v23
	v_mul_f32_e32 v11, v11, v24
	v_mul_f32_e32 v5, v5, v27
	s_andn2_b64 vcc, exec, s[2:3]
	v_mul_f32_e32 v16, v19, v16
	v_mul_f32_e32 v17, v21, v17
	v_mul_f32_e32 v15, v15, v25
	v_mul_f32_e32 v9, v9, v26
	v_mul_f32_e32 v6, v6, v7
	v_mul_f32_e32 v7, v2, v3
	v_mul_f32_e32 v3, v10, v11
	v_mul_f32_e32 v5, v4, v5
	s_mov_b64 s[2:3], -1
	v_mul_f32_e32 v16, v18, v16
	v_mul_f32_e32 v17, v20, v17
	v_mul_f32_e32 v10, v14, v15
	v_mul_f32_e32 v8, v8, v9
	v_cvt_pk_bf16_f32 v2, v16, v6
	v_cvt_pk_bf16_f32 v3, v3, v8
	v_cvt_pk_bf16_f32 v4, v17, v7
	v_cvt_pk_bf16_f32 v5, v10, v5
	global_store_dwordx4 v[12:13], v[2:5], off
	s_cbranch_vccnz .LBB0_1003
	s_andn2_b64 vcc, exec, s[36:37]
	s_cbranch_vccnz .LBB0_1002
	s_barrier
	s_branch .LBB0_1002
